# P4/P5/P6 GEMM K-loop heads pinned at phase 8 instead of 12 (padding only)
# baseline (speedup 1.0000x reference)
.LBB0_713:
	s_ashr_i32 s19, s18, 31
	s_lshl_b64 s[22:23], s[18:19], 18
	s_add_u32 s22, s52, s22
	s_addc_u32 s23, s53, s23
	s_and_b64 s[0:1], s[0:1], exec
	s_cselect_b32 s19, s23, s29
	s_cselect_b32 s38, s22, s28
	s_add_u32 s39, s28, 0x100
	v_mov_b32_e32 v0, 0
	s_addc_u32 s40, s29, 0
	s_mov_b32 s41, -2
	v_mov_b32_e32 v1, v0
	v_mov_b32_e32 v2, v0
	v_mov_b32_e32 v3, v0
	v_mov_b32_e32 v4, v0
	v_mov_b32_e32 v5, v0
	v_mov_b32_e32 v6, v0
	v_mov_b32_e32 v7, v0
	v_mov_b32_e32 v8, v0
	v_mov_b32_e32 v9, v0
	v_mov_b32_e32 v10, v0
	v_mov_b32_e32 v11, v0
	v_mov_b32_e32 v12, v0
	v_mov_b32_e32 v13, v0
	v_mov_b32_e32 v14, v0
	v_mov_b32_e32 v15, v0
	v_mov_b32_e32 v16, v0
	v_mov_b32_e32 v17, v0
	v_mov_b32_e32 v18, v0
	v_mov_b32_e32 v19, v0
	v_mov_b32_e32 v20, v0
	v_mov_b32_e32 v21, v0
	v_mov_b32_e32 v22, v0
	v_mov_b32_e32 v23, v0
	v_mov_b32_e32 v24, v0
	v_mov_b32_e32 v25, v0
	v_mov_b32_e32 v26, v0
	v_mov_b32_e32 v27, v0
	v_mov_b32_e32 v28, v0
	v_mov_b32_e32 v29, v0
	v_mov_b32_e32 v30, v0
	v_mov_b32_e32 v31, v0
	v_mov_b32_e32 v32, v0
	v_mov_b32_e32 v33, v0
	v_mov_b32_e32 v34, v0
	v_mov_b32_e32 v35, v0
	v_mov_b32_e32 v36, v0
	v_mov_b32_e32 v37, v0
	v_mov_b32_e32 v38, v0
	v_mov_b32_e32 v39, v0
	v_mov_b32_e32 v40, v0
	v_mov_b32_e32 v41, v0
	v_mov_b32_e32 v42, v0
	v_mov_b32_e32 v43, v0
	v_mov_b32_e32 v44, v0
	v_mov_b32_e32 v45, v0
	v_mov_b32_e32 v46, v0
	v_mov_b32_e32 v47, v0
	v_mov_b32_e32 v48, v0
	v_mov_b32_e32 v49, v0
	v_mov_b32_e32 v50, v0
	v_mov_b32_e32 v51, v0
	v_mov_b32_e32 v52, v0
	v_mov_b32_e32 v53, v0
	v_mov_b32_e32 v54, v0
	v_mov_b32_e32 v55, v0
	v_mov_b32_e32 v56, v0
	v_mov_b32_e32 v57, v0
	v_mov_b32_e32 v58, v0
	v_mov_b32_e32 v59, v0
	v_mov_b32_e32 v60, v0
	v_mov_b32_e32 v61, v0
	v_mov_b32_e32 v62, v0
	v_mov_b32_e32 v63, v0
	v_mov_b32_e32 v64, v0
	v_mov_b32_e32 v65, v0
	v_mov_b32_e32 v66, v0
	v_mov_b32_e32 v67, v0
	v_mov_b32_e32 v68, v0
	v_mov_b32_e32 v69, v0
	v_mov_b32_e32 v70, v0
	v_mov_b32_e32 v71, v0
	v_mov_b32_e32 v72, v0
	v_mov_b32_e32 v73, v0
	v_mov_b32_e32 v74, v0
	v_mov_b32_e32 v75, v0
	v_mov_b32_e32 v76, v0
	v_mov_b32_e32 v77, v0
	v_mov_b32_e32 v78, v0
	v_mov_b32_e32 v79, v0
	v_mov_b32_e32 v80, v0
	v_mov_b32_e32 v81, v0
	v_mov_b32_e32 v82, v0
	v_mov_b32_e32 v83, v0
	v_mov_b32_e32 v84, v0
	v_mov_b32_e32 v85, v0
	v_mov_b32_e32 v86, v0
	v_mov_b32_e32 v87, v0
	v_mov_b32_e32 v88, v0
	v_mov_b32_e32 v89, v0
	v_mov_b32_e32 v90, v0
	v_mov_b32_e32 v91, v0
	v_mov_b32_e32 v92, v0
	v_mov_b32_e32 v93, v0
	v_mov_b32_e32 v94, v0
	v_mov_b32_e32 v95, v0
	v_mov_b32_e32 v96, v0
	v_mov_b32_e32 v97, v0
	v_mov_b32_e32 v98, v0
	v_mov_b32_e32 v99, v0
	v_mov_b32_e32 v100, v0
	v_mov_b32_e32 v101, v0
	v_mov_b32_e32 v102, v0
	v_mov_b32_e32 v103, v0
	v_mov_b32_e32 v104, v0
	v_mov_b32_e32 v105, v0
	v_mov_b32_e32 v106, v0
	v_mov_b32_e32 v107, v0
	v_mov_b32_e32 v108, v0
	v_mov_b32_e32 v109, v0
	v_mov_b32_e32 v110, v0
	v_mov_b32_e32 v111, v0
	v_mov_b32_e32 v114, v0
	v_mov_b32_e32 v115, v0
	v_mov_b32_e32 v116, v0
	v_mov_b32_e32 v117, v0
	v_mov_b32_e32 v118, v0
	v_mov_b32_e32 v119, v0
	v_mov_b32_e32 v120, v0
	v_mov_b32_e32 v121, v0
	v_mov_b32_e32 v122, v0
	v_mov_b32_e32 v123, v0
	v_mov_b32_e32 v124, v0
	v_mov_b32_e32 v125, v0
	v_mov_b32_e32 v126, v0
	v_mov_b32_e32 v127, v0
	v_mov_b32_e32 v128, v0
	v_mov_b32_e32 v129, v0
	.p2align 6
	s_nop 0
	s_nop 0
.LBB0_714:
	s_add_u32 s0, s26, 0x100
	s_addc_u32 s1, s27, 0
	s_add_i32 s66, 0, 0x10000
	s_cmp_eq_u32 s41, 4
	s_cselect_b32 s35, s21, s1
	s_cselect_b32 s34, s20, s0
	s_cselect_b32 s29, s19, s40
	s_cselect_b32 s28, s38, s39
	s_add_i32 s67, 0, 0x14000
	v_add_u32_e32 v152, s66, v157
	v_add_u32_e32 v168, s67, v157
	ds_read_b128 v[130:133], v152
	ds_read_b128 v[144:147], v152 offset:1024
	ds_read_b128 v[148:151], v152 offset:2048
	ds_read_b128 v[152:155], v152 offset:3072
	ds_read_b128 v[160:163], v168
	ds_read_b128 v[164:167], v168 offset:1024
	ds_read_b128 v[176:179], v168 offset:2048
	ds_read_b128 v[180:183], v168 offset:3072
	v_lshl_add_u64 v[168:169], s[26:27], 0, v[142:143]
	s_add_i32 m0, s25, 0xc000
	ds_read_b128 v[194:197], v159
	ds_read_b128 v[198:201], v159 offset:1024
	ds_read_b128 v[202:205], v159 offset:2048
	ds_read_b128 v[206:209], v159 offset:3072
	ds_read_b128 v[210:213], v159 offset:4096
	ds_read_b128 v[214:217], v159 offset:5120
	ds_read_b128 v[218:221], v159 offset:6144
	ds_read_b128 v[222:225], v159 offset:7168
	global_load_lds_dwordx4 v[168:169], off
	v_lshl_add_u64 v[168:169], s[26:27], 0, v[140:141]
	s_add_i32 m0, s25, 0xe000
	s_nop 0
	global_load_lds_dwordx4 v[168:169], off
	s_waitcnt vmcnt(8)
	s_waitcnt lgkmcnt(0)
	s_barrier
	s_setprio 1
	s_waitcnt lgkmcnt(0)
	v_mfma_f32_16x16x32_bf16 v[126:129], v[130:133], v[194:197], v[126:129]
	v_mfma_f32_16x16x32_bf16 v[122:125], v[148:151], v[194:197], v[122:125]
	v_mfma_f32_16x16x32_bf16 v[118:121], v[130:133], v[202:205], v[118:121]
	v_mfma_f32_16x16x32_bf16 v[114:117], v[148:151], v[202:205], v[114:117]
	v_mfma_f32_16x16x32_bf16 v[108:111], v[130:133], v[210:213], v[108:111]
	v_mfma_f32_16x16x32_bf16 v[104:107], v[148:151], v[210:213], v[104:107]
	v_mfma_f32_16x16x32_bf16 v[100:103], v[130:133], v[218:221], v[100:103]
	v_mfma_f32_16x16x32_bf16 v[96:99], v[148:151], v[218:221], v[96:99]
	v_mfma_f32_16x16x32_bf16 v[126:129], v[144:147], v[198:201], v[126:129]
	v_mfma_f32_16x16x32_bf16 v[122:125], v[152:155], v[198:201], v[122:125]
	v_mfma_f32_16x16x32_bf16 v[118:121], v[144:147], v[206:209], v[118:121]
	v_mfma_f32_16x16x32_bf16 v[114:117], v[152:155], v[206:209], v[114:117]
	v_mfma_f32_16x16x32_bf16 v[108:111], v[144:147], v[214:217], v[108:111]
	v_mfma_f32_16x16x32_bf16 v[104:107], v[152:155], v[214:217], v[104:107]
	v_mfma_f32_16x16x32_bf16 v[100:103], v[144:147], v[222:225], v[100:103]
	v_mfma_f32_16x16x32_bf16 v[96:99], v[152:155], v[222:225], v[96:99]
	s_setprio 0
	s_setprio 1
	v_mfma_f32_16x16x32_bf16 v[92:95], v[160:163], v[194:197], v[92:95]
	v_mfma_f32_16x16x32_bf16 v[88:91], v[176:179], v[194:197], v[88:91]
	v_mfma_f32_16x16x32_bf16 v[84:87], v[160:163], v[202:205], v[84:87]
	v_mfma_f32_16x16x32_bf16 v[80:83], v[176:179], v[202:205], v[80:83]
	v_mfma_f32_16x16x32_bf16 v[76:79], v[160:163], v[210:213], v[76:79]
	v_mfma_f32_16x16x32_bf16 v[72:75], v[176:179], v[210:213], v[72:75]
	v_mfma_f32_16x16x32_bf16 v[68:71], v[160:163], v[218:221], v[68:71]
	v_mfma_f32_16x16x32_bf16 v[64:67], v[176:179], v[218:221], v[64:67]
	v_mfma_f32_16x16x32_bf16 v[92:95], v[164:167], v[198:201], v[92:95]
	v_mfma_f32_16x16x32_bf16 v[88:91], v[180:183], v[198:201], v[88:91]
	v_mfma_f32_16x16x32_bf16 v[84:87], v[164:167], v[206:209], v[84:87]
	v_mfma_f32_16x16x32_bf16 v[80:83], v[180:183], v[206:209], v[80:83]
	v_mfma_f32_16x16x32_bf16 v[76:79], v[164:167], v[214:217], v[76:79]
	v_mfma_f32_16x16x32_bf16 v[72:75], v[180:183], v[214:217], v[72:75]
	v_mfma_f32_16x16x32_bf16 v[68:71], v[164:167], v[222:225], v[68:71]
	v_mfma_f32_16x16x32_bf16 v[64:67], v[180:183], v[222:225], v[64:67]
	s_setprio 0
	s_barrier
	s_add_i32 s26, s66, s49
	v_lshl_add_u64 v[168:169], s[28:29], 0, v[112:113]
	s_mov_b32 m0, s26
	ds_read_b128 v[194:197], v159 offset:16384
	ds_read_b128 v[198:201], v159 offset:17408
	ds_read_b128 v[202:205], v159 offset:18432
	ds_read_b128 v[206:209], v159 offset:19456
	ds_read_b128 v[210:213], v159 offset:20480
	ds_read_b128 v[214:217], v159 offset:21504
	ds_read_b128 v[218:221], v159 offset:22528
	ds_read_b128 v[222:225], v159 offset:23552
	global_load_lds_dwordx4 v[168:169], off
	s_add_i32 m0, s26, 0x2000
	s_add_u32 s26, s28, 0x20000
	v_lshl_add_u64 v[172:173], s[28:29], 0, v[134:135]
	s_addc_u32 s27, s29, 0
	s_add_i32 s66, s67, s49
	global_load_lds_dwordx4 v[172:173], off
	v_lshl_add_u64 v[174:175], s[26:27], 0, v[112:113]
	s_mov_b32 m0, s66
	v_lshl_add_u64 v[184:185], s[34:35], 0, v[136:137]
	global_load_lds_dwordx4 v[174:175], off
	v_lshl_add_u64 v[174:175], s[26:27], 0, v[134:135]
	s_add_i32 m0, s66, 0x2000
	s_nop 0
	global_load_lds_dwordx4 v[174:175], off
	v_lshl_add_u64 v[174:175], s[34:35], 0, v[138:139]
	s_mov_b32 m0, s25
	s_nop 0
	global_load_lds_dwordx4 v[174:175], off
	s_mov_b32 m0, s55
	s_nop 0
	global_load_lds_dwordx4 v[184:185], off
	s_waitcnt vmcnt(8)
	s_waitcnt lgkmcnt(0)
	s_barrier
	s_setprio 1
	s_waitcnt lgkmcnt(0)
	v_mfma_f32_16x16x32_bf16 v[60:63], v[130:133], v[194:197], v[60:63]
	v_mfma_f32_16x16x32_bf16 v[56:59], v[148:151], v[194:197], v[56:59]
	v_mfma_f32_16x16x32_bf16 v[52:55], v[130:133], v[202:205], v[52:55]
	v_mfma_f32_16x16x32_bf16 v[48:51], v[148:151], v[202:205], v[48:51]
	v_mfma_f32_16x16x32_bf16 v[44:47], v[130:133], v[210:213], v[44:47]
	v_mfma_f32_16x16x32_bf16 v[40:43], v[148:151], v[210:213], v[40:43]
	v_mfma_f32_16x16x32_bf16 v[36:39], v[130:133], v[218:221], v[36:39]
	v_mfma_f32_16x16x32_bf16 v[32:35], v[148:151], v[218:221], v[32:35]
	v_mfma_f32_16x16x32_bf16 v[60:63], v[144:147], v[198:201], v[60:63]
	v_mfma_f32_16x16x32_bf16 v[56:59], v[152:155], v[198:201], v[56:59]
	v_mfma_f32_16x16x32_bf16 v[52:55], v[144:147], v[206:209], v[52:55]
	v_mfma_f32_16x16x32_bf16 v[48:51], v[152:155], v[206:209], v[48:51]
	v_mfma_f32_16x16x32_bf16 v[44:47], v[144:147], v[214:217], v[44:47]
	v_mfma_f32_16x16x32_bf16 v[40:43], v[152:155], v[214:217], v[40:43]
	v_mfma_f32_16x16x32_bf16 v[36:39], v[144:147], v[222:225], v[36:39]
	v_mfma_f32_16x16x32_bf16 v[32:35], v[152:155], v[222:225], v[32:35]
	s_setprio 0
	s_setprio 1
	v_mfma_f32_16x16x32_bf16 v[28:31], v[160:163], v[194:197], v[28:31]
	v_mfma_f32_16x16x32_bf16 v[24:27], v[176:179], v[194:197], v[24:27]
	v_mfma_f32_16x16x32_bf16 v[20:23], v[160:163], v[202:205], v[20:23]
	v_mfma_f32_16x16x32_bf16 v[16:19], v[176:179], v[202:205], v[16:19]
	v_mfma_f32_16x16x32_bf16 v[12:15], v[160:163], v[210:213], v[12:15]
	v_mfma_f32_16x16x32_bf16 v[8:11], v[176:179], v[210:213], v[8:11]
	v_mfma_f32_16x16x32_bf16 v[4:7], v[160:163], v[218:221], v[4:7]
	v_mfma_f32_16x16x32_bf16 v[0:3], v[176:179], v[218:221], v[0:3]
	v_mfma_f32_16x16x32_bf16 v[28:31], v[164:167], v[198:201], v[28:31]
	v_mfma_f32_16x16x32_bf16 v[24:27], v[180:183], v[198:201], v[24:27]
	v_mfma_f32_16x16x32_bf16 v[20:23], v[164:167], v[206:209], v[20:23]
	v_mfma_f32_16x16x32_bf16 v[16:19], v[180:183], v[206:209], v[16:19]
	v_mfma_f32_16x16x32_bf16 v[12:15], v[164:167], v[214:217], v[12:15]
	v_mfma_f32_16x16x32_bf16 v[8:11], v[180:183], v[214:217], v[8:11]
	v_mfma_f32_16x16x32_bf16 v[4:7], v[164:167], v[222:225], v[4:7]
	v_mfma_f32_16x16x32_bf16 v[0:3], v[180:183], v[222:225], v[0:3]
	s_setprio 0
	s_barrier
	s_add_i32 s66, 0, 0x18000
	s_add_i32 s67, 0, 0x1c000
	v_add_u32_e32 v152, s66, v157
	v_add_u32_e32 v180, s67, v157
	ds_read_b128 v[130:133], v152
	ds_read_b128 v[144:147], v152 offset:1024
	ds_read_b128 v[148:151], v152 offset:2048
	ds_read_b128 v[152:155], v152 offset:3072
	ds_read_b128 v[160:163], v180
	ds_read_b128 v[164:167], v180 offset:1024
	ds_read_b128 v[176:179], v180 offset:2048
	ds_read_b128 v[180:183], v180 offset:3072
	s_add_u32 s26, s34, 0x1c0000
	s_addc_u32 s27, s35, 0
	s_mov_b32 m0, s56
	v_lshl_add_u64 v[186:187], s[26:27], 0, v[138:139]
	ds_read_b128 v[194:197], v159 offset:32768
	ds_read_b128 v[198:201], v159 offset:33792
	ds_read_b128 v[202:205], v159 offset:34816
	ds_read_b128 v[206:209], v159 offset:35840
	ds_read_b128 v[210:213], v159 offset:36864
	ds_read_b128 v[214:217], v159 offset:37888
	ds_read_b128 v[218:221], v159 offset:38912
	ds_read_b128 v[222:225], v159 offset:39936
	global_load_lds_dwordx4 v[186:187], off
	v_lshl_add_u64 v[186:187], s[26:27], 0, v[136:137]
	s_mov_b32 m0, s57
	s_nop 0
	global_load_lds_dwordx4 v[186:187], off
	s_waitcnt vmcnt(8)
	s_waitcnt lgkmcnt(0)
	s_barrier
	s_setprio 1
	s_waitcnt lgkmcnt(0)
	v_mfma_f32_16x16x32_bf16 v[126:129], v[130:133], v[194:197], v[126:129]
	v_mfma_f32_16x16x32_bf16 v[122:125], v[148:151], v[194:197], v[122:125]
	v_mfma_f32_16x16x32_bf16 v[118:121], v[130:133], v[202:205], v[118:121]
	v_mfma_f32_16x16x32_bf16 v[114:117], v[148:151], v[202:205], v[114:117]
	v_mfma_f32_16x16x32_bf16 v[108:111], v[130:133], v[210:213], v[108:111]
	v_mfma_f32_16x16x32_bf16 v[104:107], v[148:151], v[210:213], v[104:107]
	v_mfma_f32_16x16x32_bf16 v[100:103], v[130:133], v[218:221], v[100:103]
	v_mfma_f32_16x16x32_bf16 v[96:99], v[148:151], v[218:221], v[96:99]
	v_mfma_f32_16x16x32_bf16 v[126:129], v[144:147], v[198:201], v[126:129]
	v_mfma_f32_16x16x32_bf16 v[122:125], v[152:155], v[198:201], v[122:125]
	v_mfma_f32_16x16x32_bf16 v[118:121], v[144:147], v[206:209], v[118:121]
	v_mfma_f32_16x16x32_bf16 v[114:117], v[152:155], v[206:209], v[114:117]
	v_mfma_f32_16x16x32_bf16 v[108:111], v[144:147], v[214:217], v[108:111]
	v_mfma_f32_16x16x32_bf16 v[104:107], v[152:155], v[214:217], v[104:107]
	v_mfma_f32_16x16x32_bf16 v[100:103], v[144:147], v[222:225], v[100:103]
	v_mfma_f32_16x16x32_bf16 v[96:99], v[152:155], v[222:225], v[96:99]
	s_setprio 0
	s_setprio 1
	v_mfma_f32_16x16x32_bf16 v[92:95], v[160:163], v[194:197], v[92:95]
	v_mfma_f32_16x16x32_bf16 v[88:91], v[176:179], v[194:197], v[88:91]
	v_mfma_f32_16x16x32_bf16 v[84:87], v[160:163], v[202:205], v[84:87]
	v_mfma_f32_16x16x32_bf16 v[80:83], v[176:179], v[202:205], v[80:83]
	v_mfma_f32_16x16x32_bf16 v[76:79], v[160:163], v[210:213], v[76:79]
	v_mfma_f32_16x16x32_bf16 v[72:75], v[176:179], v[210:213], v[72:75]
	v_mfma_f32_16x16x32_bf16 v[68:71], v[160:163], v[218:221], v[68:71]
	v_mfma_f32_16x16x32_bf16 v[64:67], v[176:179], v[218:221], v[64:67]
	v_mfma_f32_16x16x32_bf16 v[92:95], v[164:167], v[198:201], v[92:95]
	v_mfma_f32_16x16x32_bf16 v[88:91], v[180:183], v[198:201], v[88:91]
	v_mfma_f32_16x16x32_bf16 v[84:87], v[164:167], v[206:209], v[84:87]
	v_mfma_f32_16x16x32_bf16 v[80:83], v[180:183], v[206:209], v[80:83]
	v_mfma_f32_16x16x32_bf16 v[76:79], v[164:167], v[214:217], v[76:79]
	v_mfma_f32_16x16x32_bf16 v[72:75], v[180:183], v[214:217], v[72:75]
	v_mfma_f32_16x16x32_bf16 v[68:71], v[164:167], v[222:225], v[68:71]
	v_mfma_f32_16x16x32_bf16 v[64:67], v[180:183], v[222:225], v[64:67]
	s_setprio 0
	s_barrier
	s_add_i32 s26, s66, s49
	v_lshl_add_u64 v[168:169], v[168:169], 0, s[86:87]
	s_mov_b32 m0, s26
	ds_read_b128 v[194:197], v159 offset:49152
	ds_read_b128 v[198:201], v159 offset:50176
	ds_read_b128 v[202:205], v159 offset:51200
	ds_read_b128 v[206:209], v159 offset:52224
	ds_read_b128 v[210:213], v159 offset:53248
	ds_read_b128 v[214:217], v159 offset:54272
	ds_read_b128 v[218:221], v159 offset:55296
	ds_read_b128 v[222:225], v159 offset:56320
	global_load_lds_dwordx4 v[168:169], off
	s_add_i32 m0, s26, 0x2000
	s_add_u32 s26, s28, 0x20080
	v_lshl_add_u64 v[168:169], v[172:173], 0, s[86:87]
	s_addc_u32 s27, s29, 0
	s_add_i32 s28, s67, s49
	global_load_lds_dwordx4 v[168:169], off
	v_lshl_add_u64 v[168:169], s[26:27], 0, v[112:113]
	s_mov_b32 m0, s28
	s_nop 0
	global_load_lds_dwordx4 v[168:169], off
	v_lshl_add_u64 v[168:169], s[26:27], 0, v[134:135]
	s_add_i32 m0, s28, 0x2000
	s_nop 0
	global_load_lds_dwordx4 v[168:169], off
	v_lshl_add_u64 v[168:169], v[174:175], 0, s[86:87]
	s_mov_b32 m0, s58
	s_nop 0
	global_load_lds_dwordx4 v[168:169], off
	v_lshl_add_u64 v[168:169], v[184:185], 0, s[86:87]
	s_mov_b32 m0, s59
	s_nop 0
	global_load_lds_dwordx4 v[168:169], off
	s_waitcnt vmcnt(8)
	s_waitcnt lgkmcnt(0)
	s_barrier
	s_setprio 1
	s_waitcnt lgkmcnt(0)
	v_mfma_f32_16x16x32_bf16 v[60:63], v[130:133], v[194:197], v[60:63]
	v_mfma_f32_16x16x32_bf16 v[56:59], v[148:151], v[194:197], v[56:59]
	v_mfma_f32_16x16x32_bf16 v[52:55], v[130:133], v[202:205], v[52:55]
	v_mfma_f32_16x16x32_bf16 v[48:51], v[148:151], v[202:205], v[48:51]
	v_mfma_f32_16x16x32_bf16 v[44:47], v[130:133], v[210:213], v[44:47]
	v_mfma_f32_16x16x32_bf16 v[40:43], v[148:151], v[210:213], v[40:43]
	v_mfma_f32_16x16x32_bf16 v[36:39], v[130:133], v[218:221], v[36:39]
	v_mfma_f32_16x16x32_bf16 v[32:35], v[148:151], v[218:221], v[32:35]
	v_mfma_f32_16x16x32_bf16 v[60:63], v[144:147], v[198:201], v[60:63]
	v_mfma_f32_16x16x32_bf16 v[56:59], v[152:155], v[198:201], v[56:59]
	v_mfma_f32_16x16x32_bf16 v[52:55], v[144:147], v[206:209], v[52:55]
	v_mfma_f32_16x16x32_bf16 v[48:51], v[152:155], v[206:209], v[48:51]
	v_mfma_f32_16x16x32_bf16 v[44:47], v[144:147], v[214:217], v[44:47]
	v_mfma_f32_16x16x32_bf16 v[40:43], v[152:155], v[214:217], v[40:43]
	v_mfma_f32_16x16x32_bf16 v[36:39], v[144:147], v[222:225], v[36:39]
	v_mfma_f32_16x16x32_bf16 v[32:35], v[152:155], v[222:225], v[32:35]
	s_setprio 0
	s_setprio 1
	v_mfma_f32_16x16x32_bf16 v[28:31], v[160:163], v[194:197], v[28:31]
	v_mfma_f32_16x16x32_bf16 v[24:27], v[176:179], v[194:197], v[24:27]
	v_mfma_f32_16x16x32_bf16 v[20:23], v[160:163], v[202:205], v[20:23]
	v_mfma_f32_16x16x32_bf16 v[16:19], v[176:179], v[202:205], v[16:19]
	v_mfma_f32_16x16x32_bf16 v[12:15], v[160:163], v[210:213], v[12:15]
	v_mfma_f32_16x16x32_bf16 v[8:11], v[176:179], v[210:213], v[8:11]
	v_mfma_f32_16x16x32_bf16 v[4:7], v[160:163], v[218:221], v[4:7]
	v_mfma_f32_16x16x32_bf16 v[0:3], v[176:179], v[218:221], v[0:3]
	v_mfma_f32_16x16x32_bf16 v[28:31], v[164:167], v[198:201], v[28:31]
	v_mfma_f32_16x16x32_bf16 v[24:27], v[180:183], v[198:201], v[24:27]
	v_mfma_f32_16x16x32_bf16 v[20:23], v[164:167], v[206:209], v[20:23]
	v_mfma_f32_16x16x32_bf16 v[16:19], v[180:183], v[206:209], v[16:19]
	v_mfma_f32_16x16x32_bf16 v[12:15], v[164:167], v[214:217], v[12:15]
	v_mfma_f32_16x16x32_bf16 v[8:11], v[180:183], v[214:217], v[8:11]
	v_mfma_f32_16x16x32_bf16 v[4:7], v[164:167], v[222:225], v[4:7]
	v_mfma_f32_16x16x32_bf16 v[0:3], v[180:183], v[222:225], v[0:3]
	s_setprio 0
	s_barrier
	s_add_i32 s41, s41, 2
	s_add_u32 s39, s39, 0x100
	s_addc_u32 s40, s40, 0
	s_cmp_gt_u32 s41, 5
	s_mov_b64 s[26:27], s[0:1]
	s_cbranch_scc0 .LBB0_714
	s_and_b64 vcc, exec, s[16:17]
	v_readlane_b32 s38, v253, 49
	s_movk_i32 s39, 0x4200
	s_movk_i32 s40, 0x1fff
	s_mov_b32 s41, 0xffff
	s_cbranch_vccz .LBB0_717
	s_barrier

.LBB0_736:
	s_ashr_i32 s13, s12, 31
	s_lshl_b64 s[16:17], s[12:13], 18
	s_add_u32 s16, s28, s16
	s_addc_u32 s17, s29, s17
	s_and_b64 s[0:1], s[0:1], exec
	s_cselect_b32 s13, s17, s23
	s_cselect_b32 s38, s16, s22
	s_add_u32 s39, s22, 0x100
	v_mov_b32_e32 v0, 0
	s_addc_u32 s40, s23, 0
	s_mov_b32 s41, -2
	v_mov_b32_e32 v1, v0
	v_mov_b32_e32 v2, v0
	v_mov_b32_e32 v3, v0
	v_mov_b32_e32 v4, v0
	v_mov_b32_e32 v5, v0
	v_mov_b32_e32 v6, v0
	v_mov_b32_e32 v7, v0
	v_mov_b32_e32 v8, v0
	v_mov_b32_e32 v9, v0
	v_mov_b32_e32 v10, v0
	v_mov_b32_e32 v11, v0
	v_mov_b32_e32 v12, v0
	v_mov_b32_e32 v13, v0
	v_mov_b32_e32 v14, v0
	v_mov_b32_e32 v15, v0
	v_mov_b32_e32 v16, v0
	v_mov_b32_e32 v17, v0
	v_mov_b32_e32 v18, v0
	v_mov_b32_e32 v19, v0
	v_mov_b32_e32 v20, v0
	v_mov_b32_e32 v21, v0
	v_mov_b32_e32 v22, v0
	v_mov_b32_e32 v23, v0
	v_mov_b32_e32 v24, v0
	v_mov_b32_e32 v25, v0
	v_mov_b32_e32 v26, v0
	v_mov_b32_e32 v27, v0
	v_mov_b32_e32 v28, v0
	v_mov_b32_e32 v29, v0
	v_mov_b32_e32 v30, v0
	v_mov_b32_e32 v31, v0
	v_mov_b32_e32 v64, v0
	v_mov_b32_e32 v65, v0
	v_mov_b32_e32 v66, v0
	v_mov_b32_e32 v67, v0
	v_mov_b32_e32 v68, v0
	v_mov_b32_e32 v69, v0
	v_mov_b32_e32 v70, v0
	v_mov_b32_e32 v71, v0
	v_mov_b32_e32 v72, v0
	v_mov_b32_e32 v73, v0
	v_mov_b32_e32 v74, v0
	v_mov_b32_e32 v75, v0
	v_mov_b32_e32 v76, v0
	v_mov_b32_e32 v77, v0
	v_mov_b32_e32 v78, v0
	v_mov_b32_e32 v79, v0
	v_mov_b32_e32 v88, v0
	v_mov_b32_e32 v89, v0
	v_mov_b32_e32 v90, v0
	v_mov_b32_e32 v91, v0
	v_mov_b32_e32 v92, v0
	v_mov_b32_e32 v93, v0
	v_mov_b32_e32 v94, v0
	v_mov_b32_e32 v95, v0
	v_mov_b32_e32 v96, v0
	v_mov_b32_e32 v97, v0
	v_mov_b32_e32 v98, v0
	v_mov_b32_e32 v99, v0
	v_mov_b32_e32 v100, v0
	v_mov_b32_e32 v101, v0
	v_mov_b32_e32 v102, v0
	v_mov_b32_e32 v103, v0
	v_mov_b32_e32 v32, v0
	v_mov_b32_e32 v33, v0
	v_mov_b32_e32 v34, v0
	v_mov_b32_e32 v35, v0
	v_mov_b32_e32 v36, v0
	v_mov_b32_e32 v37, v0
	v_mov_b32_e32 v38, v0
	v_mov_b32_e32 v39, v0
	v_mov_b32_e32 v40, v0
	v_mov_b32_e32 v41, v0
	v_mov_b32_e32 v42, v0
	v_mov_b32_e32 v43, v0
	v_mov_b32_e32 v44, v0
	v_mov_b32_e32 v45, v0
	v_mov_b32_e32 v46, v0
	v_mov_b32_e32 v47, v0
	v_mov_b32_e32 v48, v0
	v_mov_b32_e32 v49, v0
	v_mov_b32_e32 v50, v0
	v_mov_b32_e32 v51, v0
	v_mov_b32_e32 v52, v0
	v_mov_b32_e32 v53, v0
	v_mov_b32_e32 v54, v0
	v_mov_b32_e32 v55, v0
	v_mov_b32_e32 v56, v0
	v_mov_b32_e32 v57, v0
	v_mov_b32_e32 v58, v0
	v_mov_b32_e32 v59, v0
	v_mov_b32_e32 v60, v0
	v_mov_b32_e32 v61, v0
	v_mov_b32_e32 v62, v0
	v_mov_b32_e32 v63, v0
	v_mov_b32_e32 v104, v0
	v_mov_b32_e32 v105, v0
	v_mov_b32_e32 v106, v0
	v_mov_b32_e32 v107, v0
	v_mov_b32_e32 v108, v0
	v_mov_b32_e32 v109, v0
	v_mov_b32_e32 v110, v0
	v_mov_b32_e32 v111, v0
	v_mov_b32_e32 v114, v0
	v_mov_b32_e32 v115, v0
	v_mov_b32_e32 v116, v0
	v_mov_b32_e32 v117, v0
	v_mov_b32_e32 v118, v0
	v_mov_b32_e32 v119, v0
	v_mov_b32_e32 v120, v0
	v_mov_b32_e32 v121, v0
	v_mov_b32_e32 v122, v0
	v_mov_b32_e32 v123, v0
	v_mov_b32_e32 v124, v0
	v_mov_b32_e32 v125, v0
	v_mov_b32_e32 v126, v0
	v_mov_b32_e32 v127, v0
	v_mov_b32_e32 v128, v0
	v_mov_b32_e32 v129, v0
	v_mov_b32_e32 v130, v0
	v_mov_b32_e32 v131, v0
	v_mov_b32_e32 v132, v0
	v_mov_b32_e32 v133, v0
	v_mov_b32_e32 v134, v0
	v_mov_b32_e32 v135, v0
	v_mov_b32_e32 v136, v0
	v_mov_b32_e32 v137, v0
	.p2align 6
	s_nop 0
	s_nop 0
.LBB0_737:
	s_add_u32 s0, s20, 0x100
	s_addc_u32 s1, s21, 0
	s_add_i32 s49, 0, 0x10000
	s_cmp_eq_u32 s41, 4
	s_cselect_b32 s25, s15, s1
	s_cselect_b32 s24, s14, s0
	s_cselect_b32 s23, s13, s40
	s_cselect_b32 s22, s38, s39
	s_add_i32 s50, 0, 0x14000
	v_add_u32_e32 v142, s49, v195
	v_add_u32_e32 v168, s50, v195
	ds_read_b128 v[80:83], v142
	ds_read_b128 v[84:87], v142 offset:1024
	ds_read_b128 v[138:141], v142 offset:2048
	ds_read_b128 v[142:145], v142 offset:3072
	ds_read_b128 v[146:149], v168
	ds_read_b128 v[150:153], v168 offset:1024
	ds_read_b128 v[164:167], v168 offset:2048
	ds_read_b128 v[176:179], v168 offset:3072
	v_lshl_add_u64 v[168:169], s[20:21], 0, v[162:163]
	s_add_i32 m0, s19, 0xc000
	ds_read_b128 v[180:183], v197
	ds_read_b128 v[198:201], v197 offset:1024
	ds_read_b128 v[202:205], v197 offset:2048
	ds_read_b128 v[206:209], v197 offset:3072
	ds_read_b128 v[210:213], v197 offset:4096
	ds_read_b128 v[214:217], v197 offset:5120
	ds_read_b128 v[218:221], v197 offset:6144
	ds_read_b128 v[222:225], v197 offset:7168
	global_load_lds_dwordx4 v[168:169], off
	v_lshl_add_u64 v[168:169], s[20:21], 0, v[160:161]
	s_add_i32 m0, s19, 0xe000
	s_nop 0
	global_load_lds_dwordx4 v[168:169], off
	s_waitcnt vmcnt(8)
	s_waitcnt lgkmcnt(0)
	s_barrier
	s_setprio 1
	s_waitcnt lgkmcnt(0)
	v_mfma_f32_16x16x32_bf16 v[134:137], v[80:83], v[180:183], v[134:137]
	v_mfma_f32_16x16x32_bf16 v[130:133], v[138:141], v[180:183], v[130:133]
	v_mfma_f32_16x16x32_bf16 v[126:129], v[80:83], v[202:205], v[126:129]
	v_mfma_f32_16x16x32_bf16 v[122:125], v[138:141], v[202:205], v[122:125]
	v_mfma_f32_16x16x32_bf16 v[118:121], v[80:83], v[210:213], v[118:121]
	v_mfma_f32_16x16x32_bf16 v[114:117], v[138:141], v[210:213], v[114:117]
	v_mfma_f32_16x16x32_bf16 v[108:111], v[80:83], v[218:221], v[108:111]
	v_mfma_f32_16x16x32_bf16 v[104:107], v[138:141], v[218:221], v[104:107]
	v_mfma_f32_16x16x32_bf16 v[134:137], v[84:87], v[198:201], v[134:137]
	v_mfma_f32_16x16x32_bf16 v[130:133], v[142:145], v[198:201], v[130:133]
	v_mfma_f32_16x16x32_bf16 v[126:129], v[84:87], v[206:209], v[126:129]
	v_mfma_f32_16x16x32_bf16 v[122:125], v[142:145], v[206:209], v[122:125]
	v_mfma_f32_16x16x32_bf16 v[118:121], v[84:87], v[214:217], v[118:121]
	v_mfma_f32_16x16x32_bf16 v[114:117], v[142:145], v[214:217], v[114:117]
	v_mfma_f32_16x16x32_bf16 v[108:111], v[84:87], v[222:225], v[108:111]
	v_mfma_f32_16x16x32_bf16 v[104:107], v[142:145], v[222:225], v[104:107]
	s_setprio 0
	s_setprio 1
	v_mfma_f32_16x16x32_bf16 v[60:63], v[146:149], v[180:183], v[60:63]
	v_mfma_f32_16x16x32_bf16 v[56:59], v[164:167], v[180:183], v[56:59]
	v_mfma_f32_16x16x32_bf16 v[52:55], v[146:149], v[202:205], v[52:55]
	v_mfma_f32_16x16x32_bf16 v[48:51], v[164:167], v[202:205], v[48:51]
	v_mfma_f32_16x16x32_bf16 v[44:47], v[146:149], v[210:213], v[44:47]
	v_mfma_f32_16x16x32_bf16 v[40:43], v[164:167], v[210:213], v[40:43]
	v_mfma_f32_16x16x32_bf16 v[36:39], v[146:149], v[218:221], v[36:39]
	v_mfma_f32_16x16x32_bf16 v[32:35], v[164:167], v[218:221], v[32:35]
	v_mfma_f32_16x16x32_bf16 v[60:63], v[150:153], v[198:201], v[60:63]
	v_mfma_f32_16x16x32_bf16 v[56:59], v[176:179], v[198:201], v[56:59]
	v_mfma_f32_16x16x32_bf16 v[52:55], v[150:153], v[206:209], v[52:55]
	v_mfma_f32_16x16x32_bf16 v[48:51], v[176:179], v[206:209], v[48:51]
	v_mfma_f32_16x16x32_bf16 v[44:47], v[150:153], v[214:217], v[44:47]
	v_mfma_f32_16x16x32_bf16 v[40:43], v[176:179], v[214:217], v[40:43]
	v_mfma_f32_16x16x32_bf16 v[36:39], v[150:153], v[222:225], v[36:39]
	v_mfma_f32_16x16x32_bf16 v[32:35], v[176:179], v[222:225], v[32:35]
	s_setprio 0
	s_barrier
	s_add_i32 s20, s49, s34
	v_lshl_add_u64 v[168:169], s[22:23], 0, v[112:113]
	s_mov_b32 m0, s20
	ds_read_b128 v[180:183], v197 offset:16384
	ds_read_b128 v[198:201], v197 offset:17408
	ds_read_b128 v[202:205], v197 offset:18432
	ds_read_b128 v[206:209], v197 offset:19456
	ds_read_b128 v[210:213], v197 offset:20480
	ds_read_b128 v[214:217], v197 offset:21504
	ds_read_b128 v[218:221], v197 offset:22528
	ds_read_b128 v[222:225], v197 offset:23552
	global_load_lds_dwordx4 v[168:169], off
	s_add_i32 m0, s20, 0x2000
	s_add_u32 s20, s22, 0x20000
	v_lshl_add_u64 v[172:173], s[22:23], 0, v[158:159]
	s_addc_u32 s21, s23, 0
	s_add_i32 s49, s50, s34
	global_load_lds_dwordx4 v[172:173], off
	v_lshl_add_u64 v[174:175], s[20:21], 0, v[112:113]
	s_mov_b32 m0, s49
	v_lshl_add_u64 v[184:185], s[24:25], 0, v[156:157]
	global_load_lds_dwordx4 v[174:175], off
	v_lshl_add_u64 v[174:175], s[20:21], 0, v[158:159]
	s_add_i32 m0, s49, 0x2000
	s_nop 0
	global_load_lds_dwordx4 v[174:175], off
	v_lshl_add_u64 v[174:175], s[24:25], 0, v[154:155]
	s_mov_b32 m0, s19
	s_nop 0
	global_load_lds_dwordx4 v[174:175], off
	s_mov_b32 m0, s35
	s_nop 0
	global_load_lds_dwordx4 v[184:185], off
	s_waitcnt vmcnt(8)
	s_waitcnt lgkmcnt(0)
	s_barrier
	s_setprio 1
	s_waitcnt lgkmcnt(0)
	v_mfma_f32_16x16x32_bf16 v[100:103], v[80:83], v[180:183], v[100:103]
	v_mfma_f32_16x16x32_bf16 v[96:99], v[138:141], v[180:183], v[96:99]
	v_mfma_f32_16x16x32_bf16 v[92:95], v[80:83], v[202:205], v[92:95]
	v_mfma_f32_16x16x32_bf16 v[88:91], v[138:141], v[202:205], v[88:91]
	v_mfma_f32_16x16x32_bf16 v[76:79], v[80:83], v[210:213], v[76:79]
	v_mfma_f32_16x16x32_bf16 v[72:75], v[138:141], v[210:213], v[72:75]
	v_mfma_f32_16x16x32_bf16 v[68:71], v[80:83], v[218:221], v[68:71]
	v_mfma_f32_16x16x32_bf16 v[64:67], v[138:141], v[218:221], v[64:67]
	v_mfma_f32_16x16x32_bf16 v[100:103], v[84:87], v[198:201], v[100:103]
	v_mfma_f32_16x16x32_bf16 v[96:99], v[142:145], v[198:201], v[96:99]
	v_mfma_f32_16x16x32_bf16 v[92:95], v[84:87], v[206:209], v[92:95]
	v_mfma_f32_16x16x32_bf16 v[88:91], v[142:145], v[206:209], v[88:91]
	v_mfma_f32_16x16x32_bf16 v[76:79], v[84:87], v[214:217], v[76:79]
	v_mfma_f32_16x16x32_bf16 v[72:75], v[142:145], v[214:217], v[72:75]
	v_mfma_f32_16x16x32_bf16 v[68:71], v[84:87], v[222:225], v[68:71]
	v_mfma_f32_16x16x32_bf16 v[64:67], v[142:145], v[222:225], v[64:67]
	s_setprio 0
	s_setprio 1
	v_mfma_f32_16x16x32_bf16 v[28:31], v[146:149], v[180:183], v[28:31]
	v_mfma_f32_16x16x32_bf16 v[24:27], v[164:167], v[180:183], v[24:27]
	v_mfma_f32_16x16x32_bf16 v[20:23], v[146:149], v[202:205], v[20:23]
	v_mfma_f32_16x16x32_bf16 v[16:19], v[164:167], v[202:205], v[16:19]
	v_mfma_f32_16x16x32_bf16 v[12:15], v[146:149], v[210:213], v[12:15]
	v_mfma_f32_16x16x32_bf16 v[8:11], v[164:167], v[210:213], v[8:11]
	v_mfma_f32_16x16x32_bf16 v[4:7], v[146:149], v[218:221], v[4:7]
	v_mfma_f32_16x16x32_bf16 v[0:3], v[164:167], v[218:221], v[0:3]
	v_mfma_f32_16x16x32_bf16 v[28:31], v[150:153], v[198:201], v[28:31]
	v_mfma_f32_16x16x32_bf16 v[24:27], v[176:179], v[198:201], v[24:27]
	v_mfma_f32_16x16x32_bf16 v[20:23], v[150:153], v[206:209], v[20:23]
	v_mfma_f32_16x16x32_bf16 v[16:19], v[176:179], v[206:209], v[16:19]
	v_mfma_f32_16x16x32_bf16 v[12:15], v[150:153], v[214:217], v[12:15]
	v_mfma_f32_16x16x32_bf16 v[8:11], v[176:179], v[214:217], v[8:11]
	v_mfma_f32_16x16x32_bf16 v[4:7], v[150:153], v[222:225], v[4:7]
	v_mfma_f32_16x16x32_bf16 v[0:3], v[176:179], v[222:225], v[0:3]
	s_setprio 0
	s_barrier
	s_add_i32 s49, 0, 0x18000
	s_add_i32 s50, 0, 0x1c000
	v_add_u32_e32 v142, s49, v195
	v_add_u32_e32 v176, s50, v195
	ds_read_b128 v[80:83], v142
	ds_read_b128 v[84:87], v142 offset:1024
	ds_read_b128 v[138:141], v142 offset:2048
	ds_read_b128 v[142:145], v142 offset:3072
	ds_read_b128 v[146:149], v176
	ds_read_b128 v[150:153], v176 offset:1024
	ds_read_b128 v[164:167], v176 offset:2048
	ds_read_b128 v[176:179], v176 offset:3072
	s_add_u32 s20, s24, 0x1c0000
	s_addc_u32 s21, s25, 0
	s_mov_b32 m0, s36
	v_lshl_add_u64 v[186:187], s[20:21], 0, v[154:155]
	ds_read_b128 v[180:183], v197 offset:32768
	ds_read_b128 v[198:201], v197 offset:33792
	ds_read_b128 v[202:205], v197 offset:34816
	ds_read_b128 v[206:209], v197 offset:35840
	ds_read_b128 v[210:213], v197 offset:36864
	ds_read_b128 v[214:217], v197 offset:37888
	ds_read_b128 v[218:221], v197 offset:38912
	ds_read_b128 v[222:225], v197 offset:39936
	global_load_lds_dwordx4 v[186:187], off
	v_lshl_add_u64 v[186:187], s[20:21], 0, v[156:157]
	s_mov_b32 m0, s37
	s_nop 0
	global_load_lds_dwordx4 v[186:187], off
	s_waitcnt vmcnt(8)
	s_waitcnt lgkmcnt(0)
	s_barrier
	s_setprio 1
	s_waitcnt lgkmcnt(0)
	v_mfma_f32_16x16x32_bf16 v[134:137], v[80:83], v[180:183], v[134:137]
	v_mfma_f32_16x16x32_bf16 v[130:133], v[138:141], v[180:183], v[130:133]
	v_mfma_f32_16x16x32_bf16 v[126:129], v[80:83], v[202:205], v[126:129]
	v_mfma_f32_16x16x32_bf16 v[122:125], v[138:141], v[202:205], v[122:125]
	v_mfma_f32_16x16x32_bf16 v[118:121], v[80:83], v[210:213], v[118:121]
	v_mfma_f32_16x16x32_bf16 v[114:117], v[138:141], v[210:213], v[114:117]
	v_mfma_f32_16x16x32_bf16 v[108:111], v[80:83], v[218:221], v[108:111]
	v_mfma_f32_16x16x32_bf16 v[104:107], v[138:141], v[218:221], v[104:107]
	v_mfma_f32_16x16x32_bf16 v[134:137], v[84:87], v[198:201], v[134:137]
	v_mfma_f32_16x16x32_bf16 v[130:133], v[142:145], v[198:201], v[130:133]
	v_mfma_f32_16x16x32_bf16 v[126:129], v[84:87], v[206:209], v[126:129]
	v_mfma_f32_16x16x32_bf16 v[122:125], v[142:145], v[206:209], v[122:125]
	v_mfma_f32_16x16x32_bf16 v[118:121], v[84:87], v[214:217], v[118:121]
	v_mfma_f32_16x16x32_bf16 v[114:117], v[142:145], v[214:217], v[114:117]
	v_mfma_f32_16x16x32_bf16 v[108:111], v[84:87], v[222:225], v[108:111]
	v_mfma_f32_16x16x32_bf16 v[104:107], v[142:145], v[222:225], v[104:107]
	s_setprio 0
	s_setprio 1
	v_mfma_f32_16x16x32_bf16 v[60:63], v[146:149], v[180:183], v[60:63]
	v_mfma_f32_16x16x32_bf16 v[56:59], v[164:167], v[180:183], v[56:59]
	v_mfma_f32_16x16x32_bf16 v[52:55], v[146:149], v[202:205], v[52:55]
	v_mfma_f32_16x16x32_bf16 v[48:51], v[164:167], v[202:205], v[48:51]
	v_mfma_f32_16x16x32_bf16 v[44:47], v[146:149], v[210:213], v[44:47]
	v_mfma_f32_16x16x32_bf16 v[40:43], v[164:167], v[210:213], v[40:43]
	v_mfma_f32_16x16x32_bf16 v[36:39], v[146:149], v[218:221], v[36:39]
	v_mfma_f32_16x16x32_bf16 v[32:35], v[164:167], v[218:221], v[32:35]
	v_mfma_f32_16x16x32_bf16 v[60:63], v[150:153], v[198:201], v[60:63]
	v_mfma_f32_16x16x32_bf16 v[56:59], v[176:179], v[198:201], v[56:59]
	v_mfma_f32_16x16x32_bf16 v[52:55], v[150:153], v[206:209], v[52:55]
	v_mfma_f32_16x16x32_bf16 v[48:51], v[176:179], v[206:209], v[48:51]
	v_mfma_f32_16x16x32_bf16 v[44:47], v[150:153], v[214:217], v[44:47]
	v_mfma_f32_16x16x32_bf16 v[40:43], v[176:179], v[214:217], v[40:43]
	v_mfma_f32_16x16x32_bf16 v[36:39], v[150:153], v[222:225], v[36:39]
	v_mfma_f32_16x16x32_bf16 v[32:35], v[176:179], v[222:225], v[32:35]
	s_setprio 0
	s_barrier
	s_add_i32 s20, s49, s34
	v_lshl_add_u64 v[168:169], v[168:169], 0, s[86:87]
	s_mov_b32 m0, s20
	ds_read_b128 v[180:183], v197 offset:49152
	ds_read_b128 v[198:201], v197 offset:50176
	ds_read_b128 v[202:205], v197 offset:51200
	ds_read_b128 v[206:209], v197 offset:52224
	ds_read_b128 v[210:213], v197 offset:53248
	ds_read_b128 v[214:217], v197 offset:54272
	ds_read_b128 v[218:221], v197 offset:55296
	ds_read_b128 v[222:225], v197 offset:56320
	global_load_lds_dwordx4 v[168:169], off
	s_add_i32 m0, s20, 0x2000
	s_add_u32 s20, s22, 0x20080
	v_lshl_add_u64 v[168:169], v[172:173], 0, s[86:87]
	s_addc_u32 s21, s23, 0
	s_add_i32 s22, s50, s34
	global_load_lds_dwordx4 v[168:169], off
	v_lshl_add_u64 v[168:169], s[20:21], 0, v[112:113]
	s_mov_b32 m0, s22
	s_nop 0
	global_load_lds_dwordx4 v[168:169], off
	v_lshl_add_u64 v[168:169], s[20:21], 0, v[158:159]
	s_add_i32 m0, s22, 0x2000
	s_nop 0
	global_load_lds_dwordx4 v[168:169], off
	v_lshl_add_u64 v[168:169], v[174:175], 0, s[86:87]
	s_mov_b32 m0, s45
	s_nop 0
	global_load_lds_dwordx4 v[168:169], off
	v_lshl_add_u64 v[168:169], v[184:185], 0, s[86:87]
	s_mov_b32 m0, s46
	s_nop 0
	global_load_lds_dwordx4 v[168:169], off
	s_waitcnt vmcnt(8)
	s_waitcnt lgkmcnt(0)
	s_barrier
	s_setprio 1
	s_waitcnt lgkmcnt(0)
	v_mfma_f32_16x16x32_bf16 v[100:103], v[80:83], v[180:183], v[100:103]
	v_mfma_f32_16x16x32_bf16 v[96:99], v[138:141], v[180:183], v[96:99]
	v_mfma_f32_16x16x32_bf16 v[92:95], v[80:83], v[202:205], v[92:95]
	v_mfma_f32_16x16x32_bf16 v[88:91], v[138:141], v[202:205], v[88:91]
	v_mfma_f32_16x16x32_bf16 v[76:79], v[80:83], v[210:213], v[76:79]
	v_mfma_f32_16x16x32_bf16 v[72:75], v[138:141], v[210:213], v[72:75]
	v_mfma_f32_16x16x32_bf16 v[68:71], v[80:83], v[218:221], v[68:71]
	v_mfma_f32_16x16x32_bf16 v[64:67], v[138:141], v[218:221], v[64:67]
	v_mfma_f32_16x16x32_bf16 v[100:103], v[84:87], v[198:201], v[100:103]
	v_mfma_f32_16x16x32_bf16 v[96:99], v[142:145], v[198:201], v[96:99]
	v_mfma_f32_16x16x32_bf16 v[92:95], v[84:87], v[206:209], v[92:95]
	v_mfma_f32_16x16x32_bf16 v[88:91], v[142:145], v[206:209], v[88:91]
	v_mfma_f32_16x16x32_bf16 v[76:79], v[84:87], v[214:217], v[76:79]
	v_mfma_f32_16x16x32_bf16 v[72:75], v[142:145], v[214:217], v[72:75]
	v_mfma_f32_16x16x32_bf16 v[68:71], v[84:87], v[222:225], v[68:71]
	v_mfma_f32_16x16x32_bf16 v[64:67], v[142:145], v[222:225], v[64:67]
	s_setprio 0
	s_setprio 1
	v_mfma_f32_16x16x32_bf16 v[28:31], v[146:149], v[180:183], v[28:31]
	v_mfma_f32_16x16x32_bf16 v[24:27], v[164:167], v[180:183], v[24:27]
	v_mfma_f32_16x16x32_bf16 v[20:23], v[146:149], v[202:205], v[20:23]
	v_mfma_f32_16x16x32_bf16 v[16:19], v[164:167], v[202:205], v[16:19]
	v_mfma_f32_16x16x32_bf16 v[12:15], v[146:149], v[210:213], v[12:15]
	v_mfma_f32_16x16x32_bf16 v[8:11], v[164:167], v[210:213], v[8:11]
	v_mfma_f32_16x16x32_bf16 v[4:7], v[146:149], v[218:221], v[4:7]
	v_mfma_f32_16x16x32_bf16 v[0:3], v[164:167], v[218:221], v[0:3]
	v_mfma_f32_16x16x32_bf16 v[28:31], v[150:153], v[198:201], v[28:31]
	v_mfma_f32_16x16x32_bf16 v[24:27], v[176:179], v[198:201], v[24:27]
	v_mfma_f32_16x16x32_bf16 v[20:23], v[150:153], v[206:209], v[20:23]
	v_mfma_f32_16x16x32_bf16 v[16:19], v[176:179], v[206:209], v[16:19]
	v_mfma_f32_16x16x32_bf16 v[12:15], v[150:153], v[214:217], v[12:15]
	v_mfma_f32_16x16x32_bf16 v[8:11], v[176:179], v[214:217], v[8:11]
	v_mfma_f32_16x16x32_bf16 v[4:7], v[150:153], v[222:225], v[4:7]
	v_mfma_f32_16x16x32_bf16 v[0:3], v[176:179], v[222:225], v[0:3]
	s_setprio 0
	s_barrier
	s_add_i32 s41, s41, 2
	s_add_u32 s39, s39, 0x100
	s_addc_u32 s40, s40, 0
	s_cmp_gt_u32 s41, 5
	s_mov_b64 s[20:21], s[0:1]
	s_cbranch_scc0 .LBB0_737
	s_and_b64 vcc, exec, s[10:11]
	s_cbranch_vccz .LBB0_740
	s_barrier

.LBB0_798:
	s_ashr_i32 s15, s14, 31
	s_lshl_b64 s[18:19], s[14:15], 18
	s_add_u32 s18, s34, s18
	s_addc_u32 s19, s35, s19
	s_and_b64 s[0:1], s[0:1], exec
	s_cselect_b32 s15, s19, s25
	s_cselect_b32 s38, s18, s24
	s_add_u32 s39, s24, 0x100
	v_mov_b32_e32 v0, 0
	s_addc_u32 s40, s25, 0
	s_mov_b32 s41, -2
	v_mov_b32_e32 v1, v0
	v_mov_b32_e32 v2, v0
	v_mov_b32_e32 v3, v0
	v_mov_b32_e32 v4, v0
	v_mov_b32_e32 v5, v0
	v_mov_b32_e32 v6, v0
	v_mov_b32_e32 v7, v0
	v_mov_b32_e32 v8, v0
	v_mov_b32_e32 v9, v0
	v_mov_b32_e32 v10, v0
	v_mov_b32_e32 v11, v0
	v_mov_b32_e32 v12, v0
	v_mov_b32_e32 v13, v0
	v_mov_b32_e32 v14, v0
	v_mov_b32_e32 v15, v0
	v_mov_b32_e32 v16, v0
	v_mov_b32_e32 v17, v0
	v_mov_b32_e32 v18, v0
	v_mov_b32_e32 v19, v0
	v_mov_b32_e32 v20, v0
	v_mov_b32_e32 v21, v0
	v_mov_b32_e32 v22, v0
	v_mov_b32_e32 v23, v0
	v_mov_b32_e32 v24, v0
	v_mov_b32_e32 v25, v0
	v_mov_b32_e32 v26, v0
	v_mov_b32_e32 v27, v0
	v_mov_b32_e32 v28, v0
	v_mov_b32_e32 v29, v0
	v_mov_b32_e32 v30, v0
	v_mov_b32_e32 v31, v0
	v_mov_b32_e32 v32, v0
	v_mov_b32_e32 v33, v0
	v_mov_b32_e32 v34, v0
	v_mov_b32_e32 v35, v0
	v_mov_b32_e32 v36, v0
	v_mov_b32_e32 v37, v0
	v_mov_b32_e32 v38, v0
	v_mov_b32_e32 v39, v0
	v_mov_b32_e32 v40, v0
	v_mov_b32_e32 v41, v0
	v_mov_b32_e32 v42, v0
	v_mov_b32_e32 v43, v0
	v_mov_b32_e32 v44, v0
	v_mov_b32_e32 v45, v0
	v_mov_b32_e32 v46, v0
	v_mov_b32_e32 v47, v0
	v_mov_b32_e32 v48, v0
	v_mov_b32_e32 v49, v0
	v_mov_b32_e32 v50, v0
	v_mov_b32_e32 v51, v0
	v_mov_b32_e32 v52, v0
	v_mov_b32_e32 v53, v0
	v_mov_b32_e32 v54, v0
	v_mov_b32_e32 v55, v0
	v_mov_b32_e32 v56, v0
	v_mov_b32_e32 v57, v0
	v_mov_b32_e32 v58, v0
	v_mov_b32_e32 v59, v0
	v_mov_b32_e32 v60, v0
	v_mov_b32_e32 v61, v0
	v_mov_b32_e32 v62, v0
	v_mov_b32_e32 v63, v0
	v_mov_b32_e32 v64, v0
	v_mov_b32_e32 v65, v0
	v_mov_b32_e32 v66, v0
	v_mov_b32_e32 v67, v0
	v_mov_b32_e32 v68, v0
	v_mov_b32_e32 v69, v0
	v_mov_b32_e32 v70, v0
	v_mov_b32_e32 v71, v0
	v_mov_b32_e32 v72, v0
	v_mov_b32_e32 v73, v0
	v_mov_b32_e32 v74, v0
	v_mov_b32_e32 v75, v0
	v_mov_b32_e32 v76, v0
	v_mov_b32_e32 v77, v0
	v_mov_b32_e32 v78, v0
	v_mov_b32_e32 v79, v0
	v_mov_b32_e32 v80, v0
	v_mov_b32_e32 v81, v0
	v_mov_b32_e32 v82, v0
	v_mov_b32_e32 v83, v0
	v_mov_b32_e32 v84, v0
	v_mov_b32_e32 v85, v0
	v_mov_b32_e32 v86, v0
	v_mov_b32_e32 v87, v0
	v_mov_b32_e32 v88, v0
	v_mov_b32_e32 v89, v0
	v_mov_b32_e32 v90, v0
	v_mov_b32_e32 v91, v0
	v_mov_b32_e32 v92, v0
	v_mov_b32_e32 v93, v0
	v_mov_b32_e32 v94, v0
	v_mov_b32_e32 v95, v0
	v_mov_b32_e32 v96, v0
	v_mov_b32_e32 v97, v0
	v_mov_b32_e32 v98, v0
	v_mov_b32_e32 v99, v0
	v_mov_b32_e32 v100, v0
	v_mov_b32_e32 v101, v0
	v_mov_b32_e32 v102, v0
	v_mov_b32_e32 v103, v0
	v_mov_b32_e32 v104, v0
	v_mov_b32_e32 v105, v0
	v_mov_b32_e32 v106, v0
	v_mov_b32_e32 v107, v0
	v_mov_b32_e32 v108, v0
	v_mov_b32_e32 v109, v0
	v_mov_b32_e32 v110, v0
	v_mov_b32_e32 v111, v0
	v_mov_b32_e32 v114, v0
	v_mov_b32_e32 v115, v0
	v_mov_b32_e32 v116, v0
	v_mov_b32_e32 v117, v0
	v_mov_b32_e32 v118, v0
	v_mov_b32_e32 v119, v0
	v_mov_b32_e32 v120, v0
	v_mov_b32_e32 v121, v0
	v_mov_b32_e32 v122, v0
	v_mov_b32_e32 v123, v0
	v_mov_b32_e32 v124, v0
	v_mov_b32_e32 v125, v0
	v_mov_b32_e32 v126, v0
	v_mov_b32_e32 v127, v0
	v_mov_b32_e32 v128, v0
	v_mov_b32_e32 v129, v0
	.p2align 6
	s_nop 0
	s_nop 0
.LBB0_799:
	s_add_u32 s0, s22, 0x100
	s_addc_u32 s1, s23, 0
	s_add_i32 s50, 0, 0x10000
	s_cmp_eq_u32 s41, 4
	s_cselect_b32 s27, s17, s1
	s_cselect_b32 s26, s16, s0
	s_cselect_b32 s25, s15, s40
	s_cselect_b32 s24, s38, s39
	s_add_i32 s51, 0, 0x14000
	v_add_u32_e32 v152, s50, v195
	v_add_u32_e32 v168, s51, v195
	ds_read_b128 v[130:133], v152
	ds_read_b128 v[134:137], v152 offset:1024
	ds_read_b128 v[138:141], v152 offset:2048
	ds_read_b128 v[152:155], v152 offset:3072
	ds_read_b128 v[156:159], v168
	ds_read_b128 v[160:163], v168 offset:1024
	ds_read_b128 v[164:167], v168 offset:2048
	ds_read_b128 v[176:179], v168 offset:3072
	v_lshl_add_u64 v[168:169], s[22:23], 0, v[150:151]
	s_add_i32 m0, s21, 0xc000
	ds_read_b128 v[180:183], v197
	ds_read_b128 v[198:201], v197 offset:1024
	ds_read_b128 v[202:205], v197 offset:2048
	ds_read_b128 v[206:209], v197 offset:3072
	ds_read_b128 v[210:213], v197 offset:4096
	ds_read_b128 v[214:217], v197 offset:5120
	ds_read_b128 v[218:221], v197 offset:6144
	ds_read_b128 v[222:225], v197 offset:7168
	global_load_lds_dwordx4 v[168:169], off
	v_lshl_add_u64 v[168:169], s[22:23], 0, v[148:149]
	s_add_i32 m0, s21, 0xe000
	s_nop 0
	global_load_lds_dwordx4 v[168:169], off
	s_waitcnt vmcnt(8)
	s_waitcnt lgkmcnt(0)
	s_barrier
	s_setprio 1
	s_waitcnt lgkmcnt(0)
	v_mfma_f32_16x16x32_bf16 v[126:129], v[130:133], v[180:183], v[126:129]
	v_mfma_f32_16x16x32_bf16 v[122:125], v[138:141], v[180:183], v[122:125]
	v_mfma_f32_16x16x32_bf16 v[118:121], v[130:133], v[202:205], v[118:121]
	v_mfma_f32_16x16x32_bf16 v[114:117], v[138:141], v[202:205], v[114:117]
	v_mfma_f32_16x16x32_bf16 v[108:111], v[130:133], v[210:213], v[108:111]
	v_mfma_f32_16x16x32_bf16 v[104:107], v[138:141], v[210:213], v[104:107]
	v_mfma_f32_16x16x32_bf16 v[100:103], v[130:133], v[218:221], v[100:103]
	v_mfma_f32_16x16x32_bf16 v[96:99], v[138:141], v[218:221], v[96:99]
	v_mfma_f32_16x16x32_bf16 v[126:129], v[134:137], v[198:201], v[126:129]
	v_mfma_f32_16x16x32_bf16 v[122:125], v[152:155], v[198:201], v[122:125]
	v_mfma_f32_16x16x32_bf16 v[118:121], v[134:137], v[206:209], v[118:121]
	v_mfma_f32_16x16x32_bf16 v[114:117], v[152:155], v[206:209], v[114:117]
	v_mfma_f32_16x16x32_bf16 v[108:111], v[134:137], v[214:217], v[108:111]
	v_mfma_f32_16x16x32_bf16 v[104:107], v[152:155], v[214:217], v[104:107]
	v_mfma_f32_16x16x32_bf16 v[100:103], v[134:137], v[222:225], v[100:103]
	v_mfma_f32_16x16x32_bf16 v[96:99], v[152:155], v[222:225], v[96:99]
	s_setprio 0
	s_setprio 1
	v_mfma_f32_16x16x32_bf16 v[92:95], v[156:159], v[180:183], v[92:95]
	v_mfma_f32_16x16x32_bf16 v[88:91], v[164:167], v[180:183], v[88:91]
	v_mfma_f32_16x16x32_bf16 v[84:87], v[156:159], v[202:205], v[84:87]
	v_mfma_f32_16x16x32_bf16 v[80:83], v[164:167], v[202:205], v[80:83]
	v_mfma_f32_16x16x32_bf16 v[76:79], v[156:159], v[210:213], v[76:79]
	v_mfma_f32_16x16x32_bf16 v[72:75], v[164:167], v[210:213], v[72:75]
	v_mfma_f32_16x16x32_bf16 v[68:71], v[156:159], v[218:221], v[68:71]
	v_mfma_f32_16x16x32_bf16 v[64:67], v[164:167], v[218:221], v[64:67]
	v_mfma_f32_16x16x32_bf16 v[92:95], v[160:163], v[198:201], v[92:95]
	v_mfma_f32_16x16x32_bf16 v[88:91], v[176:179], v[198:201], v[88:91]
	v_mfma_f32_16x16x32_bf16 v[84:87], v[160:163], v[206:209], v[84:87]
	v_mfma_f32_16x16x32_bf16 v[80:83], v[176:179], v[206:209], v[80:83]
	v_mfma_f32_16x16x32_bf16 v[76:79], v[160:163], v[214:217], v[76:79]
	v_mfma_f32_16x16x32_bf16 v[72:75], v[176:179], v[214:217], v[72:75]
	v_mfma_f32_16x16x32_bf16 v[68:71], v[160:163], v[222:225], v[68:71]
	v_mfma_f32_16x16x32_bf16 v[64:67], v[176:179], v[222:225], v[64:67]
	s_setprio 0
	s_barrier
	s_add_i32 s22, s50, s36
	v_lshl_add_u64 v[168:169], s[24:25], 0, v[112:113]
	s_mov_b32 m0, s22
	ds_read_b128 v[180:183], v197 offset:16384
	ds_read_b128 v[198:201], v197 offset:17408
	ds_read_b128 v[202:205], v197 offset:18432
	ds_read_b128 v[206:209], v197 offset:19456
	ds_read_b128 v[210:213], v197 offset:20480
	ds_read_b128 v[214:217], v197 offset:21504
	ds_read_b128 v[218:221], v197 offset:22528
	ds_read_b128 v[222:225], v197 offset:23552
	global_load_lds_dwordx4 v[168:169], off
	s_add_i32 m0, s22, 0x2000
	s_add_u32 s22, s24, 0x20000
	v_lshl_add_u64 v[172:173], s[24:25], 0, v[142:143]
	s_addc_u32 s23, s25, 0
	s_add_i32 s50, s51, s36
	global_load_lds_dwordx4 v[172:173], off
	v_lshl_add_u64 v[174:175], s[22:23], 0, v[112:113]
	s_mov_b32 m0, s50
	v_lshl_add_u64 v[184:185], s[26:27], 0, v[144:145]
	global_load_lds_dwordx4 v[174:175], off
	v_lshl_add_u64 v[174:175], s[22:23], 0, v[142:143]
	s_add_i32 m0, s50, 0x2000
	s_nop 0
	global_load_lds_dwordx4 v[174:175], off
	v_lshl_add_u64 v[174:175], s[26:27], 0, v[146:147]
	s_mov_b32 m0, s21
	s_nop 0
	global_load_lds_dwordx4 v[174:175], off
	s_mov_b32 m0, s37
	s_nop 0
	global_load_lds_dwordx4 v[184:185], off
	s_waitcnt vmcnt(8)
	s_waitcnt lgkmcnt(0)
	s_barrier
	s_setprio 1
	s_waitcnt lgkmcnt(0)
	v_mfma_f32_16x16x32_bf16 v[60:63], v[130:133], v[180:183], v[60:63]
	v_mfma_f32_16x16x32_bf16 v[56:59], v[138:141], v[180:183], v[56:59]
	v_mfma_f32_16x16x32_bf16 v[52:55], v[130:133], v[202:205], v[52:55]
	v_mfma_f32_16x16x32_bf16 v[48:51], v[138:141], v[202:205], v[48:51]
	v_mfma_f32_16x16x32_bf16 v[44:47], v[130:133], v[210:213], v[44:47]
	v_mfma_f32_16x16x32_bf16 v[40:43], v[138:141], v[210:213], v[40:43]
	v_mfma_f32_16x16x32_bf16 v[36:39], v[130:133], v[218:221], v[36:39]
	v_mfma_f32_16x16x32_bf16 v[32:35], v[138:141], v[218:221], v[32:35]
	v_mfma_f32_16x16x32_bf16 v[60:63], v[134:137], v[198:201], v[60:63]
	v_mfma_f32_16x16x32_bf16 v[56:59], v[152:155], v[198:201], v[56:59]
	v_mfma_f32_16x16x32_bf16 v[52:55], v[134:137], v[206:209], v[52:55]
	v_mfma_f32_16x16x32_bf16 v[48:51], v[152:155], v[206:209], v[48:51]
	v_mfma_f32_16x16x32_bf16 v[44:47], v[134:137], v[214:217], v[44:47]
	v_mfma_f32_16x16x32_bf16 v[40:43], v[152:155], v[214:217], v[40:43]
	v_mfma_f32_16x16x32_bf16 v[36:39], v[134:137], v[222:225], v[36:39]
	v_mfma_f32_16x16x32_bf16 v[32:35], v[152:155], v[222:225], v[32:35]
	s_setprio 0
	s_setprio 1
	v_mfma_f32_16x16x32_bf16 v[28:31], v[156:159], v[180:183], v[28:31]
	v_mfma_f32_16x16x32_bf16 v[24:27], v[164:167], v[180:183], v[24:27]
	v_mfma_f32_16x16x32_bf16 v[20:23], v[156:159], v[202:205], v[20:23]
	v_mfma_f32_16x16x32_bf16 v[16:19], v[164:167], v[202:205], v[16:19]
	v_mfma_f32_16x16x32_bf16 v[12:15], v[156:159], v[210:213], v[12:15]
	v_mfma_f32_16x16x32_bf16 v[8:11], v[164:167], v[210:213], v[8:11]
	v_mfma_f32_16x16x32_bf16 v[4:7], v[156:159], v[218:221], v[4:7]
	v_mfma_f32_16x16x32_bf16 v[0:3], v[164:167], v[218:221], v[0:3]
	v_mfma_f32_16x16x32_bf16 v[28:31], v[160:163], v[198:201], v[28:31]
	v_mfma_f32_16x16x32_bf16 v[24:27], v[176:179], v[198:201], v[24:27]
	v_mfma_f32_16x16x32_bf16 v[20:23], v[160:163], v[206:209], v[20:23]
	v_mfma_f32_16x16x32_bf16 v[16:19], v[176:179], v[206:209], v[16:19]
	v_mfma_f32_16x16x32_bf16 v[12:15], v[160:163], v[214:217], v[12:15]
	v_mfma_f32_16x16x32_bf16 v[8:11], v[176:179], v[214:217], v[8:11]
	v_mfma_f32_16x16x32_bf16 v[4:7], v[160:163], v[222:225], v[4:7]
	v_mfma_f32_16x16x32_bf16 v[0:3], v[176:179], v[222:225], v[0:3]
	s_setprio 0
	s_barrier
	s_add_i32 s50, 0, 0x18000
	s_add_i32 s51, 0, 0x1c000
	v_add_u32_e32 v152, s50, v195
	v_add_u32_e32 v176, s51, v195
	ds_read_b128 v[130:133], v152
	ds_read_b128 v[134:137], v152 offset:1024
	ds_read_b128 v[138:141], v152 offset:2048
	ds_read_b128 v[152:155], v152 offset:3072
	ds_read_b128 v[156:159], v176
	ds_read_b128 v[160:163], v176 offset:1024
	ds_read_b128 v[164:167], v176 offset:2048
	ds_read_b128 v[176:179], v176 offset:3072
	s_add_u32 s22, s26, 0x1c0000
	s_addc_u32 s23, s27, 0
	s_mov_b32 m0, s44
	v_lshl_add_u64 v[186:187], s[22:23], 0, v[146:147]
	ds_read_b128 v[180:183], v197 offset:32768
	ds_read_b128 v[198:201], v197 offset:33792
	ds_read_b128 v[202:205], v197 offset:34816
	ds_read_b128 v[206:209], v197 offset:35840
	ds_read_b128 v[210:213], v197 offset:36864
	ds_read_b128 v[214:217], v197 offset:37888
	ds_read_b128 v[218:221], v197 offset:38912
	ds_read_b128 v[222:225], v197 offset:39936
	global_load_lds_dwordx4 v[186:187], off
	v_lshl_add_u64 v[186:187], s[22:23], 0, v[144:145]
	s_mov_b32 m0, s45
	s_nop 0
	global_load_lds_dwordx4 v[186:187], off
	s_waitcnt vmcnt(8)
	s_waitcnt lgkmcnt(0)
	s_barrier
	s_setprio 1
	s_waitcnt lgkmcnt(0)
	v_mfma_f32_16x16x32_bf16 v[126:129], v[130:133], v[180:183], v[126:129]
	v_mfma_f32_16x16x32_bf16 v[122:125], v[138:141], v[180:183], v[122:125]
	v_mfma_f32_16x16x32_bf16 v[118:121], v[130:133], v[202:205], v[118:121]
	v_mfma_f32_16x16x32_bf16 v[114:117], v[138:141], v[202:205], v[114:117]
	v_mfma_f32_16x16x32_bf16 v[108:111], v[130:133], v[210:213], v[108:111]
	v_mfma_f32_16x16x32_bf16 v[104:107], v[138:141], v[210:213], v[104:107]
	v_mfma_f32_16x16x32_bf16 v[100:103], v[130:133], v[218:221], v[100:103]
	v_mfma_f32_16x16x32_bf16 v[96:99], v[138:141], v[218:221], v[96:99]
	v_mfma_f32_16x16x32_bf16 v[126:129], v[134:137], v[198:201], v[126:129]
	v_mfma_f32_16x16x32_bf16 v[122:125], v[152:155], v[198:201], v[122:125]
	v_mfma_f32_16x16x32_bf16 v[118:121], v[134:137], v[206:209], v[118:121]
	v_mfma_f32_16x16x32_bf16 v[114:117], v[152:155], v[206:209], v[114:117]
	v_mfma_f32_16x16x32_bf16 v[108:111], v[134:137], v[214:217], v[108:111]
	v_mfma_f32_16x16x32_bf16 v[104:107], v[152:155], v[214:217], v[104:107]
	v_mfma_f32_16x16x32_bf16 v[100:103], v[134:137], v[222:225], v[100:103]
	v_mfma_f32_16x16x32_bf16 v[96:99], v[152:155], v[222:225], v[96:99]
	s_setprio 0
	s_setprio 1
	v_mfma_f32_16x16x32_bf16 v[92:95], v[156:159], v[180:183], v[92:95]
	v_mfma_f32_16x16x32_bf16 v[88:91], v[164:167], v[180:183], v[88:91]
	v_mfma_f32_16x16x32_bf16 v[84:87], v[156:159], v[202:205], v[84:87]
	v_mfma_f32_16x16x32_bf16 v[80:83], v[164:167], v[202:205], v[80:83]
	v_mfma_f32_16x16x32_bf16 v[76:79], v[156:159], v[210:213], v[76:79]
	v_mfma_f32_16x16x32_bf16 v[72:75], v[164:167], v[210:213], v[72:75]
	v_mfma_f32_16x16x32_bf16 v[68:71], v[156:159], v[218:221], v[68:71]
	v_mfma_f32_16x16x32_bf16 v[64:67], v[164:167], v[218:221], v[64:67]
	v_mfma_f32_16x16x32_bf16 v[92:95], v[160:163], v[198:201], v[92:95]
	v_mfma_f32_16x16x32_bf16 v[88:91], v[176:179], v[198:201], v[88:91]
	v_mfma_f32_16x16x32_bf16 v[84:87], v[160:163], v[206:209], v[84:87]
	v_mfma_f32_16x16x32_bf16 v[80:83], v[176:179], v[206:209], v[80:83]
	v_mfma_f32_16x16x32_bf16 v[76:79], v[160:163], v[214:217], v[76:79]
	v_mfma_f32_16x16x32_bf16 v[72:75], v[176:179], v[214:217], v[72:75]
	v_mfma_f32_16x16x32_bf16 v[68:71], v[160:163], v[222:225], v[68:71]
	v_mfma_f32_16x16x32_bf16 v[64:67], v[176:179], v[222:225], v[64:67]
	s_setprio 0
	s_barrier
	s_add_i32 s22, s50, s36
	v_lshl_add_u64 v[168:169], v[168:169], 0, s[86:87]
	s_mov_b32 m0, s22
	ds_read_b128 v[180:183], v197 offset:49152
	ds_read_b128 v[198:201], v197 offset:50176
	ds_read_b128 v[202:205], v197 offset:51200
	ds_read_b128 v[206:209], v197 offset:52224
	ds_read_b128 v[210:213], v197 offset:53248
	ds_read_b128 v[214:217], v197 offset:54272
	ds_read_b128 v[218:221], v197 offset:55296
	ds_read_b128 v[222:225], v197 offset:56320
	global_load_lds_dwordx4 v[168:169], off
	s_add_i32 m0, s22, 0x2000
	s_add_u32 s22, s24, 0x20080
	v_lshl_add_u64 v[168:169], v[172:173], 0, s[86:87]
	s_addc_u32 s23, s25, 0
	s_add_i32 s24, s51, s36
	global_load_lds_dwordx4 v[168:169], off
	v_lshl_add_u64 v[168:169], s[22:23], 0, v[112:113]
	s_mov_b32 m0, s24
	s_nop 0
	global_load_lds_dwordx4 v[168:169], off
	v_lshl_add_u64 v[168:169], s[22:23], 0, v[142:143]
	s_add_i32 m0, s24, 0x2000
	s_nop 0
	global_load_lds_dwordx4 v[168:169], off
	v_lshl_add_u64 v[168:169], v[174:175], 0, s[86:87]
	s_mov_b32 m0, s46
	s_nop 0
	global_load_lds_dwordx4 v[168:169], off
	v_lshl_add_u64 v[168:169], v[184:185], 0, s[86:87]
	s_mov_b32 m0, s47
	s_nop 0
	global_load_lds_dwordx4 v[168:169], off
	s_waitcnt vmcnt(8)
	s_waitcnt lgkmcnt(0)
	s_barrier
	s_setprio 1
	s_waitcnt lgkmcnt(0)
	v_mfma_f32_16x16x32_bf16 v[60:63], v[130:133], v[180:183], v[60:63]
	v_mfma_f32_16x16x32_bf16 v[56:59], v[138:141], v[180:183], v[56:59]
	v_mfma_f32_16x16x32_bf16 v[52:55], v[130:133], v[202:205], v[52:55]
	v_mfma_f32_16x16x32_bf16 v[48:51], v[138:141], v[202:205], v[48:51]
	v_mfma_f32_16x16x32_bf16 v[44:47], v[130:133], v[210:213], v[44:47]
	v_mfma_f32_16x16x32_bf16 v[40:43], v[138:141], v[210:213], v[40:43]
	v_mfma_f32_16x16x32_bf16 v[36:39], v[130:133], v[218:221], v[36:39]
	v_mfma_f32_16x16x32_bf16 v[32:35], v[138:141], v[218:221], v[32:35]
	v_mfma_f32_16x16x32_bf16 v[60:63], v[134:137], v[198:201], v[60:63]
	v_mfma_f32_16x16x32_bf16 v[56:59], v[152:155], v[198:201], v[56:59]
	v_mfma_f32_16x16x32_bf16 v[52:55], v[134:137], v[206:209], v[52:55]
	v_mfma_f32_16x16x32_bf16 v[48:51], v[152:155], v[206:209], v[48:51]
	v_mfma_f32_16x16x32_bf16 v[44:47], v[134:137], v[214:217], v[44:47]
	v_mfma_f32_16x16x32_bf16 v[40:43], v[152:155], v[214:217], v[40:43]
	v_mfma_f32_16x16x32_bf16 v[36:39], v[134:137], v[222:225], v[36:39]
	v_mfma_f32_16x16x32_bf16 v[32:35], v[152:155], v[222:225], v[32:35]
	s_setprio 0
	s_setprio 1
	v_mfma_f32_16x16x32_bf16 v[28:31], v[156:159], v[180:183], v[28:31]
	v_mfma_f32_16x16x32_bf16 v[24:27], v[164:167], v[180:183], v[24:27]
	v_mfma_f32_16x16x32_bf16 v[20:23], v[156:159], v[202:205], v[20:23]
	v_mfma_f32_16x16x32_bf16 v[16:19], v[164:167], v[202:205], v[16:19]
	v_mfma_f32_16x16x32_bf16 v[12:15], v[156:159], v[210:213], v[12:15]
	v_mfma_f32_16x16x32_bf16 v[8:11], v[164:167], v[210:213], v[8:11]
	v_mfma_f32_16x16x32_bf16 v[4:7], v[156:159], v[218:221], v[4:7]
	v_mfma_f32_16x16x32_bf16 v[0:3], v[164:167], v[218:221], v[0:3]
	v_mfma_f32_16x16x32_bf16 v[28:31], v[160:163], v[198:201], v[28:31]
	v_mfma_f32_16x16x32_bf16 v[24:27], v[176:179], v[198:201], v[24:27]
	v_mfma_f32_16x16x32_bf16 v[20:23], v[160:163], v[206:209], v[20:23]
	v_mfma_f32_16x16x32_bf16 v[16:19], v[176:179], v[206:209], v[16:19]
	v_mfma_f32_16x16x32_bf16 v[12:15], v[160:163], v[214:217], v[12:15]
	v_mfma_f32_16x16x32_bf16 v[8:11], v[176:179], v[214:217], v[8:11]
	v_mfma_f32_16x16x32_bf16 v[4:7], v[160:163], v[222:225], v[4:7]
	v_mfma_f32_16x16x32_bf16 v[0:3], v[176:179], v[222:225], v[0:3]
	s_setprio 0
	s_barrier
	s_add_i32 s41, s41, 2
	s_add_u32 s39, s39, 0x100
	s_addc_u32 s40, s40, 0
	s_cmp_gt_u32 s41, 5
	s_mov_b64 s[22:23], s[0:1]
	s_cbranch_scc0 .LBB0_799
	s_and_b64 vcc, exec, s[12:13]
	v_readlane_b32 s38, v253, 49
	s_movk_i32 s39, 0x4200
	s_movk_i32 s40, 0x1fff
	s_mov_b32 s41, 0xffff
	s_cbranch_vccz .LBB0_802
	s_barrier

.LBB0_862:
	s_ashr_i32 s15, s14, 31
	s_lshl_b64 s[16:17], s[14:15], 19
	s_add_u32 s16, s26, s16
	s_addc_u32 s17, s27, s17
	s_and_b64 s[18:19], s[2:3], exec
	s_cselect_b32 s15, s17, s23
	s_cselect_b32 s45, s16, s22
	s_ashr_i32 s9, s8, 31
	s_lshl_b64 s[18:19], s[8:9], 19
	s_add_u32 s18, s28, s18
	s_addc_u32 s19, s29, s19
	s_and_b64 s[24:25], s[2:3], exec
	s_cselect_b32 s9, s19, s21
	s_cselect_b32 s46, s18, s20
	s_add_u32 s47, s20, 0x100
	s_addc_u32 s48, s21, 0
	s_add_u32 s20, s22, 0x40080
	v_mov_b32_e32 v0, 0
	s_addc_u32 s21, s23, 0
	s_mov_b32 s49, -2
	v_mov_b32_e32 v1, v0
	v_mov_b32_e32 v2, v0
	v_mov_b32_e32 v3, v0
	v_mov_b32_e32 v4, v0
	v_mov_b32_e32 v5, v0
	v_mov_b32_e32 v6, v0
	v_mov_b32_e32 v7, v0
	v_mov_b32_e32 v8, v0
	v_mov_b32_e32 v9, v0
	v_mov_b32_e32 v10, v0
	v_mov_b32_e32 v11, v0
	v_mov_b32_e32 v12, v0
	v_mov_b32_e32 v13, v0
	v_mov_b32_e32 v14, v0
	v_mov_b32_e32 v15, v0
	v_mov_b32_e32 v16, v0
	v_mov_b32_e32 v17, v0
	v_mov_b32_e32 v18, v0
	v_mov_b32_e32 v19, v0
	v_mov_b32_e32 v20, v0
	v_mov_b32_e32 v21, v0
	v_mov_b32_e32 v22, v0
	v_mov_b32_e32 v23, v0
	v_mov_b32_e32 v24, v0
	v_mov_b32_e32 v25, v0
	v_mov_b32_e32 v26, v0
	v_mov_b32_e32 v27, v0
	v_mov_b32_e32 v28, v0
	v_mov_b32_e32 v29, v0
	v_mov_b32_e32 v30, v0
	v_mov_b32_e32 v31, v0
	v_mov_b32_e32 v72, v0
	v_mov_b32_e32 v73, v0
	v_mov_b32_e32 v74, v0
	v_mov_b32_e32 v75, v0
	v_mov_b32_e32 v76, v0
	v_mov_b32_e32 v77, v0
	v_mov_b32_e32 v78, v0
	v_mov_b32_e32 v79, v0
	v_mov_b32_e32 v80, v0
	v_mov_b32_e32 v81, v0
	v_mov_b32_e32 v82, v0
	v_mov_b32_e32 v83, v0
	v_mov_b32_e32 v84, v0
	v_mov_b32_e32 v85, v0
	v_mov_b32_e32 v86, v0
	v_mov_b32_e32 v87, v0
	v_mov_b32_e32 v88, v0
	v_mov_b32_e32 v89, v0
	v_mov_b32_e32 v90, v0
	v_mov_b32_e32 v91, v0
	v_mov_b32_e32 v92, v0
	v_mov_b32_e32 v93, v0
	v_mov_b32_e32 v94, v0
	v_mov_b32_e32 v95, v0
	v_mov_b32_e32 v96, v0
	v_mov_b32_e32 v97, v0
	v_mov_b32_e32 v98, v0
	v_mov_b32_e32 v99, v0
	v_mov_b32_e32 v100, v0
	v_mov_b32_e32 v101, v0
	v_mov_b32_e32 v102, v0
	v_mov_b32_e32 v103, v0
	v_mov_b32_e32 v32, v0
	v_mov_b32_e32 v33, v0
	v_mov_b32_e32 v34, v0
	v_mov_b32_e32 v35, v0
	v_mov_b32_e32 v36, v0
	v_mov_b32_e32 v37, v0
	v_mov_b32_e32 v38, v0
	v_mov_b32_e32 v39, v0
	v_mov_b32_e32 v40, v0
	v_mov_b32_e32 v41, v0
	v_mov_b32_e32 v42, v0
	v_mov_b32_e32 v43, v0
	v_mov_b32_e32 v44, v0
	v_mov_b32_e32 v45, v0
	v_mov_b32_e32 v46, v0
	v_mov_b32_e32 v47, v0
	v_mov_b32_e32 v56, v0
	v_mov_b32_e32 v57, v0
	v_mov_b32_e32 v58, v0
	v_mov_b32_e32 v59, v0
	v_mov_b32_e32 v60, v0
	v_mov_b32_e32 v61, v0
	v_mov_b32_e32 v62, v0
	v_mov_b32_e32 v63, v0
	v_mov_b32_e32 v64, v0
	v_mov_b32_e32 v65, v0
	v_mov_b32_e32 v66, v0
	v_mov_b32_e32 v67, v0
	v_mov_b32_e32 v68, v0
	v_mov_b32_e32 v69, v0
	v_mov_b32_e32 v70, v0
	v_mov_b32_e32 v71, v0
	v_mov_b32_e32 v104, v0
	v_mov_b32_e32 v105, v0
	v_mov_b32_e32 v106, v0
	v_mov_b32_e32 v107, v0
	v_mov_b32_e32 v108, v0
	v_mov_b32_e32 v109, v0
	v_mov_b32_e32 v110, v0
	v_mov_b32_e32 v111, v0
	v_mov_b32_e32 v114, v0
	v_mov_b32_e32 v115, v0
	v_mov_b32_e32 v116, v0
	v_mov_b32_e32 v117, v0
	v_mov_b32_e32 v118, v0
	v_mov_b32_e32 v119, v0
	v_mov_b32_e32 v120, v0
	v_mov_b32_e32 v121, v0
	v_mov_b32_e32 v130, v0
	v_mov_b32_e32 v131, v0
	v_mov_b32_e32 v132, v0
	v_mov_b32_e32 v133, v0
	v_mov_b32_e32 v134, v0
	v_mov_b32_e32 v135, v0
	v_mov_b32_e32 v136, v0
	v_mov_b32_e32 v137, v0
	v_mov_b32_e32 v138, v0
	v_mov_b32_e32 v139, v0
	v_mov_b32_e32 v140, v0
	v_mov_b32_e32 v141, v0
	v_mov_b32_e32 v142, v0
	v_mov_b32_e32 v143, v0
	v_mov_b32_e32 v144, v0
	v_mov_b32_e32 v145, v0
	.p2align 6
	s_nop 0
	s_nop 0
.LBB0_863:
	s_add_u32 s22, s20, 0xfffc0080
	s_addc_u32 s23, s21, -1
	s_add_i32 s50, 0, 0x10000
	s_cmp_eq_u32 s49, 12
	s_cselect_b32 s25, s15, s23
	s_cselect_b32 s24, s45, s22
	s_cselect_b32 s23, s9, s48
	s_cselect_b32 s22, s46, s47
	s_add_i32 s52, 0, 0x14000
	v_add_u32_e32 v126, s50, v165
	v_add_u32_e32 v169, s52, v165
	ds_read_b128 v[48:51], v126
	ds_read_b128 v[52:55], v126 offset:1024
	ds_read_b128 v[122:125], v126 offset:2048
	ds_read_b128 v[126:129], v126 offset:3072
	ds_read_b128 v[156:159], v169
	ds_read_b128 v[160:163], v169 offset:1024
	ds_read_b128 v[176:179], v169 offset:2048
	ds_read_b128 v[180:183], v169 offset:3072
	v_lshl_add_u64 v[172:173], s[20:21], 0, v[154:155]
	s_add_i32 m0, s35, 0xc000
	ds_read_b128 v[194:197], v168
	ds_read_b128 v[198:201], v168 offset:1024
	ds_read_b128 v[202:205], v168 offset:2048
	ds_read_b128 v[206:209], v168 offset:3072
	ds_read_b128 v[210:213], v168 offset:4096
	ds_read_b128 v[214:217], v168 offset:5120
	ds_read_b128 v[218:221], v168 offset:6144
	ds_read_b128 v[222:225], v168 offset:7168
	global_load_lds_dwordx4 v[172:173], off
	v_lshl_add_u64 v[172:173], s[20:21], 0, v[152:153]
	s_add_i32 m0, s35, 0xe000
	s_nop 0
	global_load_lds_dwordx4 v[172:173], off
	s_waitcnt vmcnt(8)
	s_waitcnt lgkmcnt(0)
	s_barrier
	s_setprio 1
	s_waitcnt lgkmcnt(0)
	v_mfma_f32_16x16x32_bf16 v[142:145], v[48:51], v[194:197], v[142:145]
	v_mfma_f32_16x16x32_bf16 v[138:141], v[122:125], v[194:197], v[138:141]
	v_mfma_f32_16x16x32_bf16 v[134:137], v[48:51], v[202:205], v[134:137]
	v_mfma_f32_16x16x32_bf16 v[130:133], v[122:125], v[202:205], v[130:133]
	v_mfma_f32_16x16x32_bf16 v[118:121], v[48:51], v[210:213], v[118:121]
	v_mfma_f32_16x16x32_bf16 v[114:117], v[122:125], v[210:213], v[114:117]
	v_mfma_f32_16x16x32_bf16 v[108:111], v[48:51], v[218:221], v[108:111]
	v_mfma_f32_16x16x32_bf16 v[104:107], v[122:125], v[218:221], v[104:107]
	v_mfma_f32_16x16x32_bf16 v[142:145], v[52:55], v[198:201], v[142:145]
	v_mfma_f32_16x16x32_bf16 v[138:141], v[126:129], v[198:201], v[138:141]
	v_mfma_f32_16x16x32_bf16 v[134:137], v[52:55], v[206:209], v[134:137]
	v_mfma_f32_16x16x32_bf16 v[130:133], v[126:129], v[206:209], v[130:133]
	v_mfma_f32_16x16x32_bf16 v[118:121], v[52:55], v[214:217], v[118:121]
	v_mfma_f32_16x16x32_bf16 v[114:117], v[126:129], v[214:217], v[114:117]
	v_mfma_f32_16x16x32_bf16 v[108:111], v[52:55], v[222:225], v[108:111]
	v_mfma_f32_16x16x32_bf16 v[104:107], v[126:129], v[222:225], v[104:107]
	s_setprio 0
	s_setprio 1
	v_mfma_f32_16x16x32_bf16 v[68:71], v[156:159], v[194:197], v[68:71]
	v_mfma_f32_16x16x32_bf16 v[64:67], v[176:179], v[194:197], v[64:67]
	v_mfma_f32_16x16x32_bf16 v[60:63], v[156:159], v[202:205], v[60:63]
	v_mfma_f32_16x16x32_bf16 v[56:59], v[176:179], v[202:205], v[56:59]
	v_mfma_f32_16x16x32_bf16 v[44:47], v[156:159], v[210:213], v[44:47]
	v_mfma_f32_16x16x32_bf16 v[40:43], v[176:179], v[210:213], v[40:43]
	v_mfma_f32_16x16x32_bf16 v[36:39], v[156:159], v[218:221], v[36:39]
	v_mfma_f32_16x16x32_bf16 v[32:35], v[176:179], v[218:221], v[32:35]
	v_mfma_f32_16x16x32_bf16 v[68:71], v[160:163], v[198:201], v[68:71]
	v_mfma_f32_16x16x32_bf16 v[64:67], v[180:183], v[198:201], v[64:67]
	v_mfma_f32_16x16x32_bf16 v[60:63], v[160:163], v[206:209], v[60:63]
	v_mfma_f32_16x16x32_bf16 v[56:59], v[180:183], v[206:209], v[56:59]
	v_mfma_f32_16x16x32_bf16 v[44:47], v[160:163], v[214:217], v[44:47]
	v_mfma_f32_16x16x32_bf16 v[40:43], v[180:183], v[214:217], v[40:43]
	v_mfma_f32_16x16x32_bf16 v[36:39], v[160:163], v[222:225], v[36:39]
	v_mfma_f32_16x16x32_bf16 v[32:35], v[180:183], v[222:225], v[32:35]
	s_setprio 0
	s_barrier
	s_add_i32 s50, s50, s34
	v_lshl_add_u64 v[172:173], s[22:23], 0, v[112:113]
	s_mov_b32 m0, s50
	ds_read_b128 v[194:197], v168 offset:16384
	ds_read_b128 v[198:201], v168 offset:17408
	ds_read_b128 v[202:205], v168 offset:18432
	ds_read_b128 v[206:209], v168 offset:19456
	ds_read_b128 v[210:213], v168 offset:20480
	ds_read_b128 v[214:217], v168 offset:21504
	ds_read_b128 v[218:221], v168 offset:22528
	ds_read_b128 v[222:225], v168 offset:23552
	global_load_lds_dwordx4 v[172:173], off
	s_add_i32 m0, s50, 0x2000
	s_add_u32 s50, s22, 0x40000
	v_lshl_add_u64 v[174:175], s[22:23], 0, v[146:147]
	s_addc_u32 s51, s23, 0
	s_add_i32 s52, s52, s34
	global_load_lds_dwordx4 v[174:175], off
	v_lshl_add_u64 v[184:185], s[50:51], 0, v[112:113]
	s_mov_b32 m0, s52
	v_lshl_add_u64 v[186:187], s[24:25], 0, v[148:149]
	global_load_lds_dwordx4 v[184:185], off
	v_lshl_add_u64 v[184:185], s[50:51], 0, v[146:147]
	s_add_i32 m0, s52, 0x2000
	s_nop 0
	global_load_lds_dwordx4 v[184:185], off
	v_lshl_add_u64 v[184:185], s[24:25], 0, v[150:151]
	s_mov_b32 m0, s35
	s_nop 0
	global_load_lds_dwordx4 v[184:185], off
	s_mov_b32 m0, s36
	s_nop 0
	global_load_lds_dwordx4 v[186:187], off
	s_waitcnt vmcnt(8)
	s_waitcnt lgkmcnt(0)
	s_barrier
	s_setprio 1
	s_waitcnt lgkmcnt(0)
	v_mfma_f32_16x16x32_bf16 v[100:103], v[48:51], v[194:197], v[100:103]
	v_mfma_f32_16x16x32_bf16 v[96:99], v[122:125], v[194:197], v[96:99]
	v_mfma_f32_16x16x32_bf16 v[92:95], v[48:51], v[202:205], v[92:95]
	v_mfma_f32_16x16x32_bf16 v[88:91], v[122:125], v[202:205], v[88:91]
	v_mfma_f32_16x16x32_bf16 v[84:87], v[48:51], v[210:213], v[84:87]
	v_mfma_f32_16x16x32_bf16 v[80:83], v[122:125], v[210:213], v[80:83]
	v_mfma_f32_16x16x32_bf16 v[48:51], v[48:51], v[218:221], v[76:79]
	v_mfma_f32_16x16x32_bf16 v[100:103], v[52:55], v[198:201], v[100:103]
	v_mfma_f32_16x16x32_bf16 v[96:99], v[126:129], v[198:201], v[96:99]
	v_mfma_f32_16x16x32_bf16 v[92:95], v[52:55], v[206:209], v[92:95]
	v_mfma_f32_16x16x32_bf16 v[88:91], v[126:129], v[206:209], v[88:91]
	v_mfma_f32_16x16x32_bf16 v[84:87], v[52:55], v[214:217], v[84:87]
	v_mfma_f32_16x16x32_bf16 v[80:83], v[126:129], v[214:217], v[80:83]
	v_mfma_f32_16x16x32_bf16 v[48:51], v[52:55], v[222:225], v[48:51]
	v_mfma_f32_16x16x32_bf16 v[52:55], v[122:125], v[218:221], v[72:75]
	v_mfma_f32_16x16x32_bf16 v[52:55], v[126:129], v[222:225], v[52:55]
	s_setprio 0
	s_setprio 1
	v_mfma_f32_16x16x32_bf16 v[28:31], v[156:159], v[194:197], v[28:31]
	v_mfma_f32_16x16x32_bf16 v[24:27], v[176:179], v[194:197], v[24:27]
	v_mfma_f32_16x16x32_bf16 v[20:23], v[156:159], v[202:205], v[20:23]
	v_mfma_f32_16x16x32_bf16 v[16:19], v[176:179], v[202:205], v[16:19]
	v_mfma_f32_16x16x32_bf16 v[12:15], v[156:159], v[210:213], v[12:15]
	v_mfma_f32_16x16x32_bf16 v[8:11], v[176:179], v[210:213], v[8:11]
	v_mfma_f32_16x16x32_bf16 v[4:7], v[156:159], v[218:221], v[4:7]
	v_mfma_f32_16x16x32_bf16 v[0:3], v[176:179], v[218:221], v[0:3]
	v_mfma_f32_16x16x32_bf16 v[28:31], v[160:163], v[198:201], v[28:31]
	v_mfma_f32_16x16x32_bf16 v[24:27], v[180:183], v[198:201], v[24:27]
	v_mfma_f32_16x16x32_bf16 v[20:23], v[160:163], v[206:209], v[20:23]
	v_mfma_f32_16x16x32_bf16 v[16:19], v[180:183], v[206:209], v[16:19]
	v_mfma_f32_16x16x32_bf16 v[12:15], v[160:163], v[214:217], v[12:15]
	v_mfma_f32_16x16x32_bf16 v[8:11], v[180:183], v[214:217], v[8:11]
	v_mfma_f32_16x16x32_bf16 v[4:7], v[160:163], v[222:225], v[4:7]
	v_mfma_f32_16x16x32_bf16 v[0:3], v[180:183], v[222:225], v[0:3]
	s_setprio 0
	s_barrier
	s_add_i32 s50, 0, 0x18000
	s_add_i32 s51, 0, 0x1c000
	v_add_u32_e32 v126, s50, v165
	v_add_u32_e32 v169, s51, v165
	ds_read_b128 v[72:75], v126
	ds_read_b128 v[76:79], v126 offset:1024
	ds_read_b128 v[122:125], v126 offset:2048
	ds_read_b128 v[126:129], v126 offset:3072
	ds_read_b128 v[156:159], v169
	ds_read_b128 v[160:163], v169 offset:1024
	ds_read_b128 v[176:179], v169 offset:2048
	ds_read_b128 v[180:183], v169 offset:3072
	s_add_u32 s24, s24, 0x40000
	s_addc_u32 s25, s25, 0
	s_mov_b32 m0, s37
	v_lshl_add_u64 v[226:227], s[24:25], 0, v[150:151]
	ds_read_b128 v[194:197], v168 offset:32768
	ds_read_b128 v[198:201], v168 offset:33792
	ds_read_b128 v[202:205], v168 offset:34816
	ds_read_b128 v[206:209], v168 offset:35840
	ds_read_b128 v[210:213], v168 offset:36864
	ds_read_b128 v[214:217], v168 offset:37888
	ds_read_b128 v[218:221], v168 offset:38912
	ds_read_b128 v[222:225], v168 offset:39936
	global_load_lds_dwordx4 v[226:227], off
	v_lshl_add_u64 v[226:227], s[24:25], 0, v[148:149]
	s_mov_b32 m0, s38
	s_nop 0
	global_load_lds_dwordx4 v[226:227], off
	s_waitcnt vmcnt(8)
	s_waitcnt lgkmcnt(0)
	s_barrier
	s_setprio 1
	s_waitcnt lgkmcnt(0)
	v_mfma_f32_16x16x32_bf16 v[142:145], v[72:75], v[194:197], v[142:145]
	v_mfma_f32_16x16x32_bf16 v[138:141], v[122:125], v[194:197], v[138:141]
	v_mfma_f32_16x16x32_bf16 v[134:137], v[72:75], v[202:205], v[134:137]
	v_mfma_f32_16x16x32_bf16 v[130:133], v[122:125], v[202:205], v[130:133]
	v_mfma_f32_16x16x32_bf16 v[118:121], v[72:75], v[210:213], v[118:121]
	v_mfma_f32_16x16x32_bf16 v[114:117], v[122:125], v[210:213], v[114:117]
	v_mfma_f32_16x16x32_bf16 v[108:111], v[72:75], v[218:221], v[108:111]
	v_mfma_f32_16x16x32_bf16 v[104:107], v[122:125], v[218:221], v[104:107]
	v_mfma_f32_16x16x32_bf16 v[142:145], v[76:79], v[198:201], v[142:145]
	v_mfma_f32_16x16x32_bf16 v[138:141], v[126:129], v[198:201], v[138:141]
	v_mfma_f32_16x16x32_bf16 v[134:137], v[76:79], v[206:209], v[134:137]
	v_mfma_f32_16x16x32_bf16 v[130:133], v[126:129], v[206:209], v[130:133]
	v_mfma_f32_16x16x32_bf16 v[118:121], v[76:79], v[214:217], v[118:121]
	v_mfma_f32_16x16x32_bf16 v[114:117], v[126:129], v[214:217], v[114:117]
	v_mfma_f32_16x16x32_bf16 v[108:111], v[76:79], v[222:225], v[108:111]
	v_mfma_f32_16x16x32_bf16 v[104:107], v[126:129], v[222:225], v[104:107]
	s_setprio 0
	s_setprio 1
	v_mfma_f32_16x16x32_bf16 v[68:71], v[156:159], v[194:197], v[68:71]
	v_mfma_f32_16x16x32_bf16 v[64:67], v[176:179], v[194:197], v[64:67]
	v_mfma_f32_16x16x32_bf16 v[60:63], v[156:159], v[202:205], v[60:63]
	v_mfma_f32_16x16x32_bf16 v[56:59], v[176:179], v[202:205], v[56:59]
	v_mfma_f32_16x16x32_bf16 v[44:47], v[156:159], v[210:213], v[44:47]
	v_mfma_f32_16x16x32_bf16 v[40:43], v[176:179], v[210:213], v[40:43]
	v_mfma_f32_16x16x32_bf16 v[36:39], v[156:159], v[218:221], v[36:39]
	v_mfma_f32_16x16x32_bf16 v[32:35], v[176:179], v[218:221], v[32:35]
	v_mfma_f32_16x16x32_bf16 v[68:71], v[160:163], v[198:201], v[68:71]
	v_mfma_f32_16x16x32_bf16 v[64:67], v[180:183], v[198:201], v[64:67]
	v_mfma_f32_16x16x32_bf16 v[60:63], v[160:163], v[206:209], v[60:63]
	v_mfma_f32_16x16x32_bf16 v[56:59], v[180:183], v[206:209], v[56:59]
	v_mfma_f32_16x16x32_bf16 v[44:47], v[160:163], v[214:217], v[44:47]
	v_mfma_f32_16x16x32_bf16 v[40:43], v[180:183], v[214:217], v[40:43]
	v_mfma_f32_16x16x32_bf16 v[36:39], v[160:163], v[222:225], v[36:39]
	v_mfma_f32_16x16x32_bf16 v[32:35], v[180:183], v[222:225], v[32:35]
	s_setprio 0
	s_barrier
	s_add_i32 s24, s50, s34
	v_lshl_add_u64 v[172:173], v[172:173], 0, s[86:87]
	s_mov_b32 m0, s24
	ds_read_b128 v[194:197], v168 offset:49152
	ds_read_b128 v[198:201], v168 offset:50176
	ds_read_b128 v[202:205], v168 offset:51200
	ds_read_b128 v[206:209], v168 offset:52224
	ds_read_b128 v[210:213], v168 offset:53248
	ds_read_b128 v[214:217], v168 offset:54272
	ds_read_b128 v[218:221], v168 offset:55296
	ds_read_b128 v[222:225], v168 offset:56320
	global_load_lds_dwordx4 v[172:173], off
	s_add_i32 m0, s24, 0x2000
	s_add_u32 s22, s22, 0x40080
	v_lshl_add_u64 v[172:173], v[174:175], 0, s[86:87]
	s_addc_u32 s23, s23, 0
	s_add_i32 s24, s51, s34
	global_load_lds_dwordx4 v[172:173], off
	v_lshl_add_u64 v[172:173], s[22:23], 0, v[112:113]
	s_mov_b32 m0, s24
	s_nop 0
	global_load_lds_dwordx4 v[172:173], off
	v_lshl_add_u64 v[172:173], s[22:23], 0, v[146:147]
	s_add_i32 m0, s24, 0x2000
	s_nop 0
	global_load_lds_dwordx4 v[172:173], off
	v_lshl_add_u64 v[172:173], v[184:185], 0, s[86:87]
	s_mov_b32 m0, s41
	s_nop 0
	global_load_lds_dwordx4 v[172:173], off
	v_lshl_add_u64 v[172:173], v[186:187], 0, s[86:87]
	s_mov_b32 m0, s42
	s_nop 0
	global_load_lds_dwordx4 v[172:173], off
	s_waitcnt vmcnt(8)
	s_waitcnt lgkmcnt(0)
	s_barrier
	s_setprio 1
	s_waitcnt lgkmcnt(0)
	v_mfma_f32_16x16x32_bf16 v[100:103], v[72:75], v[194:197], v[100:103]
	v_mfma_f32_16x16x32_bf16 v[92:95], v[72:75], v[202:205], v[92:95]
	v_mfma_f32_16x16x32_bf16 v[84:87], v[72:75], v[210:213], v[84:87]
	v_mfma_f32_16x16x32_bf16 v[48:51], v[72:75], v[218:221], v[48:51]
	v_mfma_f32_16x16x32_bf16 v[100:103], v[76:79], v[198:201], v[100:103]
	v_mfma_f32_16x16x32_bf16 v[96:99], v[122:125], v[194:197], v[96:99]
	v_mfma_f32_16x16x32_bf16 v[92:95], v[76:79], v[206:209], v[92:95]
	v_mfma_f32_16x16x32_bf16 v[88:91], v[122:125], v[202:205], v[88:91]
	v_mfma_f32_16x16x32_bf16 v[84:87], v[76:79], v[214:217], v[84:87]
	v_mfma_f32_16x16x32_bf16 v[80:83], v[122:125], v[210:213], v[80:83]
	v_mfma_f32_16x16x32_bf16 v[76:79], v[76:79], v[222:225], v[48:51]
	v_mfma_f32_16x16x32_bf16 v[48:51], v[122:125], v[218:221], v[52:55]
	v_mfma_f32_16x16x32_bf16 v[96:99], v[126:129], v[198:201], v[96:99]
	v_mfma_f32_16x16x32_bf16 v[88:91], v[126:129], v[206:209], v[88:91]
	v_mfma_f32_16x16x32_bf16 v[80:83], v[126:129], v[214:217], v[80:83]
	v_mfma_f32_16x16x32_bf16 v[72:75], v[126:129], v[222:225], v[48:51]
	s_setprio 0
	s_setprio 1
	v_mfma_f32_16x16x32_bf16 v[28:31], v[156:159], v[194:197], v[28:31]
	v_mfma_f32_16x16x32_bf16 v[24:27], v[176:179], v[194:197], v[24:27]
	v_mfma_f32_16x16x32_bf16 v[20:23], v[156:159], v[202:205], v[20:23]
	v_mfma_f32_16x16x32_bf16 v[16:19], v[176:179], v[202:205], v[16:19]
	v_mfma_f32_16x16x32_bf16 v[12:15], v[156:159], v[210:213], v[12:15]
	v_mfma_f32_16x16x32_bf16 v[8:11], v[176:179], v[210:213], v[8:11]
	v_mfma_f32_16x16x32_bf16 v[4:7], v[156:159], v[218:221], v[4:7]
	v_mfma_f32_16x16x32_bf16 v[0:3], v[176:179], v[218:221], v[0:3]
	v_mfma_f32_16x16x32_bf16 v[28:31], v[160:163], v[198:201], v[28:31]
	v_mfma_f32_16x16x32_bf16 v[24:27], v[180:183], v[198:201], v[24:27]
	v_mfma_f32_16x16x32_bf16 v[20:23], v[160:163], v[206:209], v[20:23]
	v_mfma_f32_16x16x32_bf16 v[16:19], v[180:183], v[206:209], v[16:19]
	v_mfma_f32_16x16x32_bf16 v[12:15], v[160:163], v[214:217], v[12:15]
	v_mfma_f32_16x16x32_bf16 v[8:11], v[180:183], v[214:217], v[8:11]
	v_mfma_f32_16x16x32_bf16 v[4:7], v[160:163], v[222:225], v[4:7]
	v_mfma_f32_16x16x32_bf16 v[0:3], v[180:183], v[222:225], v[0:3]
	s_setprio 0
	s_barrier
	s_add_i32 s49, s49, 2
	s_add_u32 s47, s47, 0x100
	s_addc_u32 s48, s48, 0
	s_add_u32 s20, s20, 0x100
	s_addc_u32 s21, s21, 0
	s_cmp_gt_u32 s49, 13
	s_cbranch_scc0 .LBB0_863
	s_and_b64 vcc, exec, s[10:11]
	s_cbranch_vccz .LBB0_866
	s_barrier
